# nt (streaming) hint on all GEMM epilogue / slab stores so output tiles do not evict the A/B panels from L2
# baseline (speedup 1.0000x reference)
.Lrk_store:
	v_ashrrev_i32_e32 v197, 31, v196
	v_lshlrev_b64 v[130:131], 13, v[196:197]
	v_lshl_add_u64 v[130:131], s[78:79], 0, v[130:131]
	v_lshlrev_b64 v[206:207], 2, v[202:203]
	v_lshl_add_u64 v[134:135], v[130:131], 0, v[206:207]
	global_store_dwordx4 v[134:135], v[126:129], off nt
	global_store_dwordx4 v[134:135], v[122:125], off offset:64 nt
	global_store_dwordx4 v[134:135], v[110:113], off offset:512 nt
	global_store_dwordx4 v[134:135], v[106:109], off offset:576 nt
	s_mov_b32 s98, 0x20000
	s_mov_b32 s99, 0
	v_lshl_add_u64 v[136:137], v[134:135], 0, s[98:99]
	global_store_dwordx4 v[136:137], v[118:121], off nt
	global_store_dwordx4 v[136:137], v[114:117], off offset:64 nt
	global_store_dwordx4 v[136:137], v[94:97], off offset:512 nt
	global_store_dwordx4 v[136:137], v[90:93], off offset:576 nt
	s_mov_b32 s98, 0x40000
	s_mov_b32 s99, 0
	v_lshl_add_u64 v[136:137], v[134:135], 0, s[98:99]
	global_store_dwordx4 v[136:137], v[102:105], off nt
	global_store_dwordx4 v[136:137], v[98:101], off offset:64 nt
	global_store_dwordx4 v[136:137], v[78:81], off offset:512 nt
	global_store_dwordx4 v[136:137], v[74:77], off offset:576 nt
	s_mov_b32 s98, 0x60000
	s_mov_b32 s99, 0
	v_lshl_add_u64 v[136:137], v[134:135], 0, s[98:99]
	global_store_dwordx4 v[136:137], v[86:89], off nt
	global_store_dwordx4 v[136:137], v[82:85], off offset:64 nt
	global_store_dwordx4 v[136:137], v[70:73], off offset:512 nt
	global_store_dwordx4 v[136:137], v[66:69], off offset:576 nt
	s_mov_b32 s98, 0x100000
	s_mov_b32 s99, 0
	v_lshl_add_u64 v[136:137], v[134:135], 0, s[98:99]
	global_store_dwordx4 v[136:137], v[62:65], off nt
	global_store_dwordx4 v[136:137], v[58:61], off offset:64 nt
	global_store_dwordx4 v[136:137], v[46:49], off offset:512 nt
	global_store_dwordx4 v[136:137], v[42:45], off offset:576 nt
	s_mov_b32 s98, 0x120000
	s_mov_b32 s99, 0
	v_lshl_add_u64 v[136:137], v[134:135], 0, s[98:99]
	global_store_dwordx4 v[136:137], v[54:57], off nt
	global_store_dwordx4 v[136:137], v[50:53], off offset:64 nt
	global_store_dwordx4 v[136:137], v[30:33], off offset:512 nt
	global_store_dwordx4 v[136:137], v[26:29], off offset:576 nt
	s_mov_b32 s98, 0x140000
	s_mov_b32 s99, 0
	v_lshl_add_u64 v[136:137], v[134:135], 0, s[98:99]
	global_store_dwordx4 v[136:137], v[38:41], off nt
	global_store_dwordx4 v[136:137], v[34:37], off offset:64 nt
	global_store_dwordx4 v[136:137], v[14:17], off offset:512 nt
	global_store_dwordx4 v[136:137], v[10:13], off offset:576 nt
	s_mov_b32 s98, 0x160000
	s_mov_b32 s99, 0
	v_lshl_add_u64 v[136:137], v[134:135], 0, s[98:99]
	global_store_dwordx4 v[136:137], v[22:25], off nt
	global_store_dwordx4 v[136:137], v[18:21], off offset:64 nt
	global_store_dwordx4 v[136:137], v[6:9], off offset:512 nt
	global_store_dwordx4 v[136:137], v[2:5], off offset:576 nt
	s_mov_b64 s[48:49], 0
	s_branch .LBB0_385

.LBB0_347:
	s_lshl_b32 s15, s54, 8
	s_add_i32 s15, s15, s86
	v_or_b32_e32 v196, s15, v188
	s_cmp_lt_i32 s58, 2
	s_mov_b64 s[48:49], -1
	s_cbranch_scc1 .LBB0_388
	s_cmp_gt_i32 s58, 2
	s_cbranch_scc0 .LBB0_374
	v_lshl_or_b32 v162, s23, 7, v224
	v_ashrrev_i32_e32 v163, 31, v162
	v_readlane_b32 s48, v244, 30
	v_lshlrev_b64 v[164:165], 2, v[162:163]
	v_readlane_b32 s49, v244, 31
	v_lshl_add_u64 v[134:135], s[92:93], 0, v[164:165]
	v_lshl_add_u64 v[158:159], s[26:27], 0, v[164:165]
	v_lshl_add_u64 v[138:139], s[48:49], 0, v[164:165]
	v_readlane_b32 s48, v244, 32
	v_readlane_b32 s49, v244, 33
	global_load_dwordx4 v[130:133], v[134:135], off offset:16
	global_load_dwordx4 v[146:149], v[134:135], off
	v_lshl_add_u64 v[142:143], s[48:49], 0, v[164:165]
	global_load_dwordx4 v[134:137], v[138:139], off offset:16
	global_load_dwordx4 v[150:153], v[138:139], off
	s_nop 0
	global_load_dwordx4 v[138:141], v[142:143], off offset:16
	global_load_dwordx4 v[154:157], v[142:143], off
	s_nop 0
	global_load_dwordx4 v[142:145], v[158:159], off offset:16
	s_nop 0
	global_load_dwordx4 v[158:161], v[158:159], off
	v_mov_b32_e32 v199, v1
	v_mov_b32_e32 v201, v1
	s_nop 0
	v_mov_b32_dpp v199, v199 row_ror:1 row_mask:0xf bank_mask:0xf
	v_mov_b32_dpp v201, v201 row_ror:2 row_mask:0xf bank_mask:0xf
	v_mov_b32_e32 v166, v199
	v_mov_b32_e32 v168, v201
	v_mov_b32_e32 v167, v199
	v_mov_b32_e32 v169, v201
	v_mov_b32_e32 v170, v199
	v_mov_b32_e32 v172, v201
	v_mov_b32_e32 v171, v199
	v_mov_b32_e32 v173, v201
	v_mov_b32_e32 v174, v199
	v_mov_b32_e32 v176, v201
	v_mov_b32_e32 v175, v199
	v_mov_b32_e32 v177, v201
	v_mov_b32_e32 v198, v199
	v_mov_b32_e32 v200, v201
	v_mov_b32_dpp v166, v126 row_shr:1 row_mask:0xf bank_mask:0xf
	v_mov_b32_dpp v168, v126 row_shr:2 row_mask:0xf bank_mask:0xf
	v_mov_b32_dpp v167, v127 row_shr:1 row_mask:0xf bank_mask:0xf
	v_mov_b32_dpp v169, v127 row_shr:2 row_mask:0xf bank_mask:0xf
	v_mov_b32_dpp v170, v128 row_shr:1 row_mask:0xf bank_mask:0xf
	v_mov_b32_dpp v172, v128 row_shr:2 row_mask:0xf bank_mask:0xf
	v_mov_b32_dpp v171, v129 row_shr:1 row_mask:0xf bank_mask:0xf
	v_mov_b32_dpp v173, v129 row_shr:2 row_mask:0xf bank_mask:0xf
	v_mov_b32_dpp v174, v122 row_shr:1 row_mask:0xf bank_mask:0xf
	v_mov_b32_dpp v176, v122 row_shr:2 row_mask:0xf bank_mask:0xf
	v_mov_b32_dpp v175, v123 row_shr:1 row_mask:0xf bank_mask:0xf
	v_mov_b32_dpp v177, v123 row_shr:2 row_mask:0xf bank_mask:0xf
	v_mov_b32_dpp v198, v124 row_shr:1 row_mask:0xf bank_mask:0xf
	v_mov_b32_dpp v200, v124 row_shr:2 row_mask:0xf bank_mask:0xf
	v_mov_b32_dpp v199, v125 row_shr:1 row_mask:0xf bank_mask:0xf
	v_mov_b32_dpp v201, v125 row_shr:2 row_mask:0xf bank_mask:0xf
	s_and_saveexec_b64 s[48:49], s[42:43]
	s_xor_b64 s[48:49], exec, s[48:49]
	s_movk_i32 s70, 0x5800
	s_cbranch_execz .LBB0_351
	s_waitcnt vmcnt(0)
	v_pk_fma_f32 v[200:201], v[132:133], v[200:201], v[144:145]
	v_pk_fma_f32 v[176:177], v[130:131], v[176:177], v[142:143]
	v_pk_fma_f32 v[198:199], v[136:137], v[198:199], v[200:201]
	v_pk_fma_f32 v[174:175], v[134:135], v[174:175], v[176:177]
	v_pk_fma_f32 v[198:199], v[124:125], v[140:141], v[198:199]
	v_pk_fma_f32 v[174:175], v[122:123], v[138:139], v[174:175]
	v_mul_f32_e32 v0, 0xbfb8aa3b, v198
	v_exp_f32_e32 v0, v0
	v_mul_f32_e32 v197, 0xbfb8aa3b, v199
	v_exp_f32_e32 v197, v197
	v_pk_fma_f32 v[172:173], v[148:149], v[172:173], v[160:161]
	v_add_f32_e32 v0, 1.0, v0
	v_rcp_f32_e32 v200, v0
	v_add_f32_e32 v197, 1.0, v197
	v_mul_f32_e32 v0, 0xbfb8aa3b, v174
	v_rcp_f32_e32 v201, v197
	v_exp_f32_e32 v0, v0
	v_mul_f32_e32 v197, 0xbfb8aa3b, v175
	v_exp_f32_e32 v197, v197
	v_pk_fma_f32 v[170:171], v[152:153], v[170:171], v[172:173]
	v_add_f32_e32 v0, 1.0, v0
	v_pk_mul_f32 v[176:177], v[198:199], v[200:201]
	v_rcp_f32_e32 v198, v0
	v_add_f32_e32 v0, 1.0, v197
	v_pk_fma_f32 v[170:171], v[128:129], v[156:157], v[170:171]
	v_pk_fma_f32 v[168:169], v[146:147], v[168:169], v[158:159]
	v_rcp_f32_e32 v199, v0
	v_mul_f32_e32 v0, 0xbfb8aa3b, v170
	v_pk_fma_f32 v[166:167], v[150:151], v[166:167], v[168:169]
	v_exp_f32_e32 v0, v0
	v_mul_f32_e32 v172, 0xbfb8aa3b, v171
	v_pk_fma_f32 v[166:167], v[126:127], v[154:155], v[166:167]
	v_exp_f32_e32 v197, v172
	v_mul_f32_e32 v168, 0xbfb8aa3b, v166
	v_exp_f32_e32 v168, v168
	v_mul_f32_e32 v169, 0xbfb8aa3b, v167
	v_exp_f32_e32 v169, v169
	v_add_f32_e32 v0, 1.0, v0
	v_pk_mul_f32 v[172:173], v[174:175], v[198:199]
	v_rcp_f32_e32 v174, v0
	v_add_f32_e32 v0, 1.0, v197
	v_rcp_f32_e32 v175, v0
	v_add_f32_e32 v0, 1.0, v168
	v_rcp_f32_e32 v168, v0
	v_add_f32_e32 v0, 1.0, v169
	v_rcp_f32_e32 v169, v0
	v_pk_mul_f32 v[170:171], v[170:171], v[174:175]
	s_movk_i32 s50, 0x2c00
	v_pk_mul_f32 v[170:171], v[112:113], v[170:171]
	v_pk_mul_f32 v[166:167], v[166:167], v[168:169]
	v_pk_mul_f32 v[176:177], v[108:109], v[176:177]
	v_pk_mul_f32 v[166:167], v[110:111], v[166:167]
	v_pk_mul_f32 v[172:173], v[106:107], v[172:173]
	v_cvt_pk_bf16_f32 v166, v166, v167
	v_cvt_pk_bf16_f32 v167, v170, v171
	v_mov_b64_e32 v[170:171], s[24:25]
	v_mad_i64_i32 v[170:171], s[50:51], v196, s50, v[170:171]
	v_cvt_pk_bf16_f32 v168, v172, v173
	v_cvt_pk_bf16_f32 v169, v176, v177
	v_lshl_add_u64 v[170:171], v[162:163], 1, v[170:171]
	global_store_dwordx4 v[170:171], v[166:169], off nt
.LBB0_351:
	s_or_saveexec_b64 s[48:49], s[48:49]
	v_readlane_b32 s50, v244, 34
	v_readlane_b32 s51, v244, 35
	v_lshl_add_u64 v[166:167], s[82:83], 0, v[164:165]
	s_nop 0
	v_lshl_add_u64 v[168:169], s[50:51], 0, v[164:165]
	s_xor_b64 exec, exec, s[48:49]
	s_cbranch_execz .LBB0_353
	s_ashr_i32 s50, s15, 4
	v_or_b32_e32 v0, s50, v188
	v_mad_i64_i32 v[164:165], s[50:51], v0, s70, v[166:167]
	v_mad_i64_i32 v[170:171], s[50:51], v0, s70, v[168:169]
	global_store_dwordx4 v[164:165], v[126:129], off nt
	global_store_dwordx4 v[164:165], v[122:125], off offset:16 nt
	global_store_dwordx4 v[170:171], v[110:113], off nt
	global_store_dwordx4 v[170:171], v[106:109], off offset:16 nt
.LBB0_353:
	s_or_b64 exec, exec, s[48:49]
	v_mov_b32_e32 v172, v1
	v_mov_b32_e32 v173, v1
	v_mov_b32_e32 v170, v1
	v_mov_b32_dpp v172, v126 row_ror:2 row_mask:0xf bank_mask:0xf
	v_mov_b32_e32 v171, v1
	v_mov_b32_dpp v173, v127 row_ror:2 row_mask:0xf bank_mask:0xf
	v_mov_b32_dpp v170, v126 row_ror:1 row_mask:0xf bank_mask:0xf
	v_mov_b32_dpp v172, v118 row_shr:2 row_mask:0xf bank_mask:0xf
	v_mov_b32_dpp v171, v127 row_ror:1 row_mask:0xf bank_mask:0xf
	v_mov_b32_dpp v173, v119 row_shr:2 row_mask:0xf bank_mask:0xf
	v_mov_b32_dpp v170, v118 row_shr:1 row_mask:0xf bank_mask:0xf
	v_mov_b32_dpp v171, v119 row_shr:1 row_mask:0xf bank_mask:0xf
	s_waitcnt vmcnt(0)
	v_pk_fma_f32 v[172:173], v[146:147], v[172:173], v[158:159]
	v_mov_b32_e32 v174, v1
	v_pk_fma_f32 v[170:171], v[150:151], v[170:171], v[172:173]
	v_mov_b32_e32 v175, v1
	v_pk_fma_f32 v[170:171], v[118:119], v[154:155], v[170:171]
	v_mov_b32_dpp v174, v128 row_ror:2 row_mask:0xf bank_mask:0xf
	v_mul_f32_e32 v172, 0xbfb8aa3b, v170
	v_mul_f32_e32 v173, 0xbfb8aa3b, v171
	v_exp_f32_e32 v172, v172
	v_exp_f32_e32 v173, v173
	v_mov_b32_dpp v175, v129 row_ror:2 row_mask:0xf bank_mask:0xf
	v_mov_b32_dpp v174, v120 row_shr:2 row_mask:0xf bank_mask:0xf
	v_add_f32_e32 v172, 1.0, v172
	v_add_f32_e32 v173, 1.0, v173
	v_rcp_f32_e32 v172, v172
	v_rcp_f32_e32 v173, v173
	v_mov_b32_dpp v175, v121 row_shr:2 row_mask:0xf bank_mask:0xf
	v_pk_fma_f32 v[174:175], v[148:149], v[174:175], v[160:161]
	v_mov_b32_e32 v176, v1
	v_pk_mul_f32 v[170:171], v[170:171], v[172:173]
	v_mov_b32_e32 v172, v1
	v_mov_b32_e32 v173, v1
	v_mov_b32_e32 v177, v1
	v_mov_b32_dpp v172, v128 row_ror:1 row_mask:0xf bank_mask:0xf
	v_mov_b32_dpp v173, v129 row_ror:1 row_mask:0xf bank_mask:0xf
	v_mov_b32_dpp v176, v122 row_ror:2 row_mask:0xf bank_mask:0xf
	v_mov_b32_dpp v172, v120 row_shr:1 row_mask:0xf bank_mask:0xf
	v_mov_b32_dpp v173, v121 row_shr:1 row_mask:0xf bank_mask:0xf
	v_pk_fma_f32 v[172:173], v[152:153], v[172:173], v[174:175]
	v_mov_b32_dpp v177, v123 row_ror:2 row_mask:0xf bank_mask:0xf
	v_pk_fma_f32 v[172:173], v[120:121], v[156:157], v[172:173]
	v_mov_b32_dpp v176, v114 row_shr:2 row_mask:0xf bank_mask:0xf
	v_mul_f32_e32 v174, 0xbfb8aa3b, v172
	v_mul_f32_e32 v175, 0xbfb8aa3b, v173
	v_exp_f32_e32 v174, v174
	v_exp_f32_e32 v175, v175
	v_mov_b32_dpp v177, v115 row_shr:2 row_mask:0xf bank_mask:0xf
	v_pk_fma_f32 v[176:177], v[130:131], v[176:177], v[142:143]
	v_add_f32_e32 v174, 1.0, v174
	v_add_f32_e32 v175, 1.0, v175
	v_rcp_f32_e32 v174, v174
	v_rcp_f32_e32 v175, v175
	v_mov_b32_e32 v198, v1
	v_mov_b32_e32 v199, v1
	v_pk_mul_f32 v[170:171], v[94:95], v[170:171]
	v_pk_mul_f32 v[172:173], v[172:173], v[174:175]
	v_mov_b32_e32 v174, v1
	v_mov_b32_e32 v175, v1
	v_mov_b32_dpp v198, v124 row_ror:2 row_mask:0xf bank_mask:0xf
	v_mov_b32_dpp v174, v122 row_ror:1 row_mask:0xf bank_mask:0xf
	v_mov_b32_dpp v175, v123 row_ror:1 row_mask:0xf bank_mask:0xf
	v_mov_b32_dpp v199, v125 row_ror:2 row_mask:0xf bank_mask:0xf
	v_mov_b32_dpp v174, v114 row_shr:1 row_mask:0xf bank_mask:0xf
	v_mov_b32_dpp v175, v115 row_shr:1 row_mask:0xf bank_mask:0xf
	v_pk_fma_f32 v[174:175], v[134:135], v[174:175], v[176:177]
	v_mov_b32_dpp v198, v116 row_shr:2 row_mask:0xf bank_mask:0xf
	v_pk_fma_f32 v[174:175], v[114:115], v[138:139], v[174:175]
	v_mov_b32_dpp v199, v117 row_shr:2 row_mask:0xf bank_mask:0xf
	v_mul_f32_e32 v176, 0xbfb8aa3b, v174
	v_mul_f32_e32 v177, 0xbfb8aa3b, v175
	v_exp_f32_e32 v176, v176
	v_exp_f32_e32 v177, v177
	v_pk_fma_f32 v[198:199], v[132:133], v[198:199], v[144:145]
	v_pk_mul_f32 v[172:173], v[96:97], v[172:173]
	v_add_f32_e32 v176, 1.0, v176
	v_add_f32_e32 v177, 1.0, v177
	v_rcp_f32_e32 v176, v176
	v_rcp_f32_e32 v177, v177
	s_cmp_gt_i32 s54, 31
	v_or_b32_e32 v0, 16, v196
	v_cvt_pk_bf16_f32 v170, v170, v171
	v_pk_mul_f32 v[174:175], v[174:175], v[176:177]
	v_mov_b32_e32 v176, v1
	v_mov_b32_e32 v177, v1
	v_pk_mul_f32 v[174:175], v[90:91], v[174:175]
	v_mov_b32_dpp v176, v124 row_ror:1 row_mask:0xf bank_mask:0xf
	v_mov_b32_dpp v177, v125 row_ror:1 row_mask:0xf bank_mask:0xf
	v_cvt_pk_bf16_f32 v171, v172, v173
	v_mov_b32_dpp v176, v116 row_shr:1 row_mask:0xf bank_mask:0xf
	v_mov_b32_dpp v177, v117 row_shr:1 row_mask:0xf bank_mask:0xf
	v_pk_fma_f32 v[176:177], v[136:137], v[176:177], v[198:199]
	v_cvt_pk_bf16_f32 v172, v174, v175
	v_pk_fma_f32 v[176:177], v[116:117], v[140:141], v[176:177]
	v_mov_b64_e32 v[174:175], s[24:25]
	v_mul_f32_e32 v197, 0xbfb8aa3b, v176
	v_exp_f32_e32 v197, v197
	s_movk_i32 s54, 0x2c00
	s_cselect_b64 s[48:49], -1, 0
	v_mad_i64_i32 v[174:175], s[54:55], v0, s54, v[174:175]
	v_add_f32_e32 v197, 1.0, v197
	v_rcp_f32_e32 v198, v197
	v_mul_f32_e32 v197, 0xbfb8aa3b, v177
	v_exp_f32_e32 v197, v197
	v_lshl_add_u64 v[164:165], v[162:163], 2, s[74:75]
	s_and_b64 s[50:51], s[44:45], s[48:49]
	v_lshl_add_u64 v[174:175], v[162:163], 1, v[174:175]
	v_add_f32_e32 v197, 1.0, v197
	v_rcp_f32_e32 v199, v197
	s_nop 0
	v_pk_mul_f32 v[176:177], v[176:177], v[198:199]
	s_nop 0
	v_pk_mul_f32 v[176:177], v[92:93], v[176:177]
	s_nop 0
	v_cvt_pk_bf16_f32 v173, v176, v177
	global_store_dwordx4 v[174:175], v[170:173], off nt
	s_and_saveexec_b64 s[54:55], s[50:51]
	s_cbranch_execz .LBB0_355
	s_ashr_i32 s15, s15, 4
	v_add_u32_e32 v0, s15, v190
	v_mad_i64_i32 v[170:171], s[56:57], v0, s70, v[164:165]
	global_store_dwordx4 v[170:171], v[118:121], off nt
	global_store_dwordx4 v[170:171], v[114:117], off offset:16 nt
.LBB0_355:
	s_or_b64 exec, exec, s[54:55]
	v_cndmask_b32_e64 v171, v118, 0, s[48:49]
	v_mov_b32_e32 v170, v1
	v_mov_b32_e32 v172, v1
	v_cndmask_b32_e64 v174, v119, 0, s[48:49]
	v_mov_b32_dpp v170, v171 row_ror:1 row_mask:0xf bank_mask:0xf
	v_mov_b32_dpp v172, v171 row_ror:2 row_mask:0xf bank_mask:0xf
	v_mov_b32_e32 v171, v1
	v_mov_b32_e32 v173, v1
	v_cndmask_b32_e64 v175, v120, 0, s[48:49]
	v_mov_b32_dpp v171, v174 row_ror:1 row_mask:0xf bank_mask:0xf
	v_mov_b32_dpp v173, v174 row_ror:2 row_mask:0xf bank_mask:0xf
	v_mov_b32_e32 v174, v1
	v_mov_b32_e32 v176, v1
	v_cndmask_b32_e64 v197, v121, 0, s[48:49]
	v_mov_b32_dpp v174, v175 row_ror:1 row_mask:0xf bank_mask:0xf
	v_mov_b32_dpp v176, v175 row_ror:2 row_mask:0xf bank_mask:0xf
	v_mov_b32_e32 v175, v1
	v_mov_b32_e32 v177, v1
	v_mov_b32_e32 v198, v1
	v_mov_b32_dpp v175, v197 row_ror:1 row_mask:0xf bank_mask:0xf
	v_mov_b32_dpp v177, v197 row_ror:2 row_mask:0xf bank_mask:0xf
	v_cndmask_b32_e64 v197, v114, 0, s[48:49]
	v_mov_b32_e32 v200, v1
	v_mov_b32_e32 v199, v1
	v_mov_b32_dpp v198, v197 row_ror:1 row_mask:0xf bank_mask:0xf
	v_mov_b32_dpp v200, v197 row_ror:2 row_mask:0xf bank_mask:0xf
	v_cndmask_b32_e64 v197, v115, 0, s[48:49]
	v_mov_b32_e32 v201, v1
	v_mov_b32_e32 v202, v1
	v_mov_b32_dpp v199, v197 row_ror:1 row_mask:0xf bank_mask:0xf
	v_mov_b32_dpp v201, v197 row_ror:2 row_mask:0xf bank_mask:0xf
	v_cndmask_b32_e64 v197, v116, 0, s[48:49]
	v_mov_b32_e32 v204, v1
	v_readlane_b32 s54, v245, 62
	v_mov_b32_dpp v202, v197 row_ror:1 row_mask:0xf bank_mask:0xf
	v_mov_b32_dpp v204, v197 row_ror:2 row_mask:0xf bank_mask:0xf
	v_cndmask_b32_e64 v197, v117, 0, s[48:49]
	v_mov_b32_e32 v203, v1
	v_mov_b32_e32 v205, v1
	v_readlane_b32 s55, v245, 63
	v_mov_b32_dpp v203, v197 row_ror:1 row_mask:0xf bank_mask:0xf
	v_mov_b32_dpp v205, v197 row_ror:2 row_mask:0xf bank_mask:0xf
	s_and_b64 s[54:55], s[54:55], s[48:49]
	v_or_b32_e32 v0, 32, v196
	v_mov_b32_dpp v170, v102 row_shr:1 row_mask:0xf bank_mask:0xf
	v_mov_b32_dpp v172, v102 row_shr:2 row_mask:0xf bank_mask:0xf
	v_mov_b32_dpp v171, v103 row_shr:1 row_mask:0xf bank_mask:0xf
	v_mov_b32_dpp v173, v103 row_shr:2 row_mask:0xf bank_mask:0xf
	v_mov_b32_dpp v174, v104 row_shr:1 row_mask:0xf bank_mask:0xf
	v_mov_b32_dpp v176, v104 row_shr:2 row_mask:0xf bank_mask:0xf
	v_mov_b32_dpp v175, v105 row_shr:1 row_mask:0xf bank_mask:0xf
	v_mov_b32_dpp v177, v105 row_shr:2 row_mask:0xf bank_mask:0xf
	v_mov_b32_dpp v198, v98 row_shr:1 row_mask:0xf bank_mask:0xf
	v_mov_b32_dpp v200, v98 row_shr:2 row_mask:0xf bank_mask:0xf
	v_mov_b32_dpp v199, v99 row_shr:1 row_mask:0xf bank_mask:0xf
	v_mov_b32_dpp v201, v99 row_shr:2 row_mask:0xf bank_mask:0xf
	v_mov_b32_dpp v202, v100 row_shr:1 row_mask:0xf bank_mask:0xf
	v_mov_b32_dpp v204, v100 row_shr:2 row_mask:0xf bank_mask:0xf
	v_mov_b32_dpp v203, v101 row_shr:1 row_mask:0xf bank_mask:0xf
	v_mov_b32_dpp v205, v101 row_shr:2 row_mask:0xf bank_mask:0xf
	s_xor_b64 s[54:55], s[54:55], -1
	s_and_saveexec_b64 s[56:57], s[54:55]
	s_xor_b64 s[56:57], exec, s[56:57]
	s_cbranch_execz .LBB0_357
	v_pk_fma_f32 v[204:205], v[132:133], v[204:205], v[144:145]
	v_pk_fma_f32 v[200:201], v[130:131], v[200:201], v[142:143]
	v_pk_fma_f32 v[202:203], v[136:137], v[202:203], v[204:205]
	v_pk_fma_f32 v[198:199], v[134:135], v[198:199], v[200:201]
	v_pk_fma_f32 v[202:203], v[100:101], v[140:141], v[202:203]
	v_pk_fma_f32 v[198:199], v[98:99], v[138:139], v[198:199]
	v_mul_f32_e32 v197, 0xbfb8aa3b, v202
	v_mul_f32_e32 v204, 0xbfb8aa3b, v203
	v_exp_f32_e32 v197, v197
	v_exp_f32_e32 v204, v204
	v_pk_fma_f32 v[176:177], v[148:149], v[176:177], v[160:161]
	v_pk_fma_f32 v[172:173], v[146:147], v[172:173], v[158:159]
	v_add_f32_e32 v197, 1.0, v197
	v_add_f32_e32 v205, 1.0, v204
	v_rcp_f32_e32 v204, v197
	v_rcp_f32_e32 v205, v205
	v_mul_f32_e32 v197, 0xbfb8aa3b, v198
	v_exp_f32_e32 v197, v197
	v_pk_fma_f32 v[174:175], v[152:153], v[174:175], v[176:177]
	v_pk_mul_f32 v[200:201], v[202:203], v[204:205]
	v_mul_f32_e32 v202, 0xbfb8aa3b, v199
	v_exp_f32_e32 v203, v202
	v_add_f32_e32 v197, 1.0, v197
	v_pk_fma_f32 v[174:175], v[104:105], v[156:157], v[174:175]
	v_pk_fma_f32 v[170:171], v[150:151], v[170:171], v[172:173]
	v_rcp_f32_e32 v202, v197
	v_add_f32_e32 v197, 1.0, v203
	v_mul_f32_e32 v176, 0xbfb8aa3b, v174
	v_pk_fma_f32 v[170:171], v[102:103], v[154:155], v[170:171]
	v_rcp_f32_e32 v203, v197
	v_exp_f32_e32 v197, v176
	v_mul_f32_e32 v176, 0xbfb8aa3b, v175
	v_mul_f32_e32 v172, 0xbfb8aa3b, v170
	v_mul_f32_e32 v173, 0xbfb8aa3b, v171
	v_exp_f32_e32 v204, v176
	v_exp_f32_e32 v172, v172
	v_exp_f32_e32 v173, v173
	v_add_f32_e32 v197, 1.0, v197
	v_pk_mul_f32 v[176:177], v[198:199], v[202:203]
	v_rcp_f32_e32 v198, v197
	v_add_f32_e32 v197, 1.0, v204
	v_add_f32_e32 v172, 1.0, v172
	v_add_f32_e32 v173, 1.0, v173
	v_rcp_f32_e32 v199, v197
	v_rcp_f32_e32 v172, v172
	v_rcp_f32_e32 v173, v173
	s_movk_i32 s15, 0x2c00
	v_pk_mul_f32 v[174:175], v[174:175], v[198:199]
	v_pk_mul_f32 v[200:201], v[76:77], v[200:201]
	v_pk_mul_f32 v[170:171], v[170:171], v[172:173]
	v_pk_mul_f32 v[174:175], v[80:81], v[174:175]
	v_pk_mul_f32 v[170:171], v[78:79], v[170:171]
	v_pk_mul_f32 v[176:177], v[74:75], v[176:177]
	v_cvt_pk_bf16_f32 v170, v170, v171
	v_cvt_pk_bf16_f32 v171, v174, v175
	v_mov_b64_e32 v[174:175], s[24:25]
	v_mad_i64_i32 v[174:175], s[68:69], v0, s15, v[174:175]
	v_cvt_pk_bf16_f32 v172, v176, v177
	v_cvt_pk_bf16_f32 v173, v200, v201
	v_lshl_add_u64 v[174:175], v[162:163], 1, v[174:175]
	global_store_dwordx4 v[174:175], v[170:173], off nt
.LBB0_357:
	s_andn2_saveexec_b64 s[56:57], s[56:57]
	s_cbranch_execz .LBB0_359
	v_ashrrev_i32_e32 v0, 5, v0
	v_lshl_or_b32 v0, v0, 1, v188
	v_mad_i64_i32 v[170:171], s[68:69], v0, s70, v[166:167]
	v_mad_i64_i32 v[172:173], s[68:69], v0, s70, v[168:169]
	global_store_dwordx4 v[170:171], v[102:105], off nt
	global_store_dwordx4 v[170:171], v[98:101], off offset:16 nt
	global_store_dwordx4 v[172:173], v[78:81], off nt
	global_store_dwordx4 v[172:173], v[74:77], off offset:16 nt
.LBB0_359:
	s_or_b64 exec, exec, s[56:57]
	v_mov_b32_e32 v172, v1
	v_mov_b32_e32 v173, v1
	v_mov_b32_e32 v170, v1
	v_mov_b32_dpp v172, v102 row_ror:2 row_mask:0xf bank_mask:0xf
	v_mov_b32_e32 v171, v1
	v_mov_b32_dpp v173, v103 row_ror:2 row_mask:0xf bank_mask:0xf
	v_mov_b32_dpp v170, v102 row_ror:1 row_mask:0xf bank_mask:0xf
	v_mov_b32_dpp v172, v86 row_shr:2 row_mask:0xf bank_mask:0xf
	v_mov_b32_dpp v171, v103 row_ror:1 row_mask:0xf bank_mask:0xf
	v_mov_b32_dpp v173, v87 row_shr:2 row_mask:0xf bank_mask:0xf
	v_mov_b32_dpp v170, v86 row_shr:1 row_mask:0xf bank_mask:0xf
	v_mov_b32_dpp v171, v87 row_shr:1 row_mask:0xf bank_mask:0xf
	v_pk_fma_f32 v[172:173], v[146:147], v[172:173], v[158:159]
	v_mov_b32_e32 v174, v1
	v_pk_fma_f32 v[170:171], v[150:151], v[170:171], v[172:173]
	v_mov_b32_e32 v175, v1
	v_pk_fma_f32 v[170:171], v[86:87], v[154:155], v[170:171]
	v_mov_b32_dpp v174, v104 row_ror:2 row_mask:0xf bank_mask:0xf
	v_mul_f32_e32 v172, 0xbfb8aa3b, v170
	v_mul_f32_e32 v173, 0xbfb8aa3b, v171
	v_exp_f32_e32 v172, v172
	v_exp_f32_e32 v173, v173
	v_mov_b32_dpp v175, v105 row_ror:2 row_mask:0xf bank_mask:0xf
	v_mov_b32_dpp v174, v88 row_shr:2 row_mask:0xf bank_mask:0xf
	v_add_f32_e32 v172, 1.0, v172
	v_add_f32_e32 v173, 1.0, v173
	v_rcp_f32_e32 v172, v172
	v_rcp_f32_e32 v173, v173
	v_mov_b32_dpp v175, v89 row_shr:2 row_mask:0xf bank_mask:0xf
	v_pk_fma_f32 v[174:175], v[148:149], v[174:175], v[160:161]
	v_mov_b32_e32 v176, v1
	v_pk_mul_f32 v[170:171], v[170:171], v[172:173]
	v_mov_b32_e32 v172, v1
	v_mov_b32_e32 v173, v1
	v_mov_b32_e32 v177, v1
	v_mov_b32_dpp v172, v104 row_ror:1 row_mask:0xf bank_mask:0xf
	v_mov_b32_dpp v173, v105 row_ror:1 row_mask:0xf bank_mask:0xf
	v_mov_b32_dpp v176, v98 row_ror:2 row_mask:0xf bank_mask:0xf
	v_mov_b32_dpp v172, v88 row_shr:1 row_mask:0xf bank_mask:0xf
	v_mov_b32_dpp v173, v89 row_shr:1 row_mask:0xf bank_mask:0xf
	v_pk_fma_f32 v[172:173], v[152:153], v[172:173], v[174:175]
	v_mov_b32_dpp v177, v99 row_ror:2 row_mask:0xf bank_mask:0xf
	v_pk_fma_f32 v[172:173], v[88:89], v[156:157], v[172:173]
	v_mov_b32_dpp v176, v82 row_shr:2 row_mask:0xf bank_mask:0xf
	v_mul_f32_e32 v174, 0xbfb8aa3b, v172
	v_mul_f32_e32 v175, 0xbfb8aa3b, v173
	v_exp_f32_e32 v174, v174
	v_exp_f32_e32 v175, v175
	v_mov_b32_dpp v177, v83 row_shr:2 row_mask:0xf bank_mask:0xf
	v_pk_fma_f32 v[176:177], v[130:131], v[176:177], v[142:143]
	v_add_f32_e32 v174, 1.0, v174
	v_add_f32_e32 v175, 1.0, v175
	v_rcp_f32_e32 v174, v174
	v_rcp_f32_e32 v175, v175
	v_mov_b32_e32 v198, v1
	v_mov_b32_e32 v199, v1
	v_pk_mul_f32 v[170:171], v[70:71], v[170:171]
	v_pk_mul_f32 v[172:173], v[172:173], v[174:175]
	v_mov_b32_e32 v174, v1
	v_mov_b32_e32 v175, v1
	v_mov_b32_dpp v198, v100 row_ror:2 row_mask:0xf bank_mask:0xf
	v_mov_b32_dpp v174, v98 row_ror:1 row_mask:0xf bank_mask:0xf
	v_mov_b32_dpp v175, v99 row_ror:1 row_mask:0xf bank_mask:0xf
	v_mov_b32_dpp v199, v101 row_ror:2 row_mask:0xf bank_mask:0xf
	v_mov_b32_dpp v174, v82 row_shr:1 row_mask:0xf bank_mask:0xf
	v_mov_b32_dpp v175, v83 row_shr:1 row_mask:0xf bank_mask:0xf
	v_pk_fma_f32 v[174:175], v[134:135], v[174:175], v[176:177]
	v_mov_b32_dpp v198, v84 row_shr:2 row_mask:0xf bank_mask:0xf
	v_pk_fma_f32 v[174:175], v[82:83], v[138:139], v[174:175]
	v_mov_b32_dpp v199, v85 row_shr:2 row_mask:0xf bank_mask:0xf
	v_mul_f32_e32 v176, 0xbfb8aa3b, v174
	v_mul_f32_e32 v177, 0xbfb8aa3b, v175
	v_exp_f32_e32 v176, v176
	v_exp_f32_e32 v177, v177
	v_pk_fma_f32 v[198:199], v[132:133], v[198:199], v[144:145]
	v_pk_mul_f32 v[172:173], v[72:73], v[172:173]
	v_add_f32_e32 v176, 1.0, v176
	v_add_f32_e32 v177, 1.0, v177
	v_rcp_f32_e32 v176, v176
	v_rcp_f32_e32 v177, v177
	v_or_b32_e32 v0, 48, v196
	v_cvt_pk_bf16_f32 v170, v170, v171
	v_cvt_pk_bf16_f32 v171, v172, v173
	v_pk_mul_f32 v[174:175], v[174:175], v[176:177]
	v_mov_b32_e32 v176, v1
	v_mov_b32_e32 v177, v1
	v_pk_mul_f32 v[174:175], v[66:67], v[174:175]
	v_mov_b32_dpp v176, v100 row_ror:1 row_mask:0xf bank_mask:0xf
	v_mov_b32_dpp v177, v101 row_ror:1 row_mask:0xf bank_mask:0xf
	v_cvt_pk_bf16_f32 v172, v174, v175
	v_mov_b32_dpp v176, v84 row_shr:1 row_mask:0xf bank_mask:0xf
	v_mov_b32_dpp v177, v85 row_shr:1 row_mask:0xf bank_mask:0xf
	v_pk_fma_f32 v[176:177], v[136:137], v[176:177], v[198:199]
	v_mov_b64_e32 v[174:175], s[24:25]
	v_pk_fma_f32 v[176:177], v[84:85], v[140:141], v[176:177]
	s_movk_i32 s15, 0x2c00
	v_mul_f32_e32 v197, 0xbfb8aa3b, v176
	v_exp_f32_e32 v197, v197
	v_mad_i64_i32 v[174:175], s[56:57], v0, s15, v[174:175]
	v_lshl_add_u64 v[174:175], v[162:163], 1, v[174:175]
	v_add_f32_e32 v197, 1.0, v197
	v_rcp_f32_e32 v198, v197
	v_mul_f32_e32 v197, 0xbfb8aa3b, v177
	v_exp_f32_e32 v197, v197
	s_nop 0
	v_add_f32_e32 v197, 1.0, v197
	v_rcp_f32_e32 v199, v197
	s_nop 0
	v_pk_mul_f32 v[176:177], v[176:177], v[198:199]
	s_nop 0
	v_pk_mul_f32 v[176:177], v[68:69], v[176:177]
	s_nop 0
	v_cvt_pk_bf16_f32 v173, v176, v177
	global_store_dwordx4 v[174:175], v[170:173], off nt
	s_and_saveexec_b64 s[56:57], s[44:45]
	s_cbranch_execz .LBB0_361
	v_ashrrev_i32_e32 v0, 5, v0
	v_lshl_add_u32 v0, v0, 1, v190
	v_mad_i64_i32 v[170:171], s[68:69], v0, s70, v[164:165]
	global_store_dwordx4 v[170:171], v[86:89], off nt
	global_store_dwordx4 v[170:171], v[82:85], off offset:16 nt
.LBB0_361:
	s_or_b64 exec, exec, s[56:57]
	v_mov_b32_e32 v203, v1
	v_mov_b32_e32 v205, v1
	v_add_u32_e32 v0, 0x80, v196
	v_mov_b32_dpp v203, v203 row_ror:1 row_mask:0xf bank_mask:0xf
	v_mov_b32_dpp v205, v205 row_ror:2 row_mask:0xf bank_mask:0xf
	v_mov_b32_e32 v170, v203
	v_mov_b32_e32 v172, v205
	v_mov_b32_e32 v171, v203
	v_mov_b32_e32 v173, v205
	v_mov_b32_e32 v174, v203
	v_mov_b32_e32 v176, v205
	v_mov_b32_e32 v175, v203
	v_mov_b32_e32 v177, v205
	v_mov_b32_e32 v198, v203
	v_mov_b32_e32 v200, v205
	v_mov_b32_e32 v199, v203
	v_mov_b32_e32 v201, v205
	v_mov_b32_e32 v202, v203
	v_mov_b32_e32 v204, v205
	v_mov_b32_dpp v170, v62 row_shr:1 row_mask:0xf bank_mask:0xf
	v_mov_b32_dpp v172, v62 row_shr:2 row_mask:0xf bank_mask:0xf
	v_mov_b32_dpp v171, v63 row_shr:1 row_mask:0xf bank_mask:0xf
	v_mov_b32_dpp v173, v63 row_shr:2 row_mask:0xf bank_mask:0xf
	v_mov_b32_dpp v174, v64 row_shr:1 row_mask:0xf bank_mask:0xf
	v_mov_b32_dpp v176, v64 row_shr:2 row_mask:0xf bank_mask:0xf
	v_mov_b32_dpp v175, v65 row_shr:1 row_mask:0xf bank_mask:0xf
	v_mov_b32_dpp v177, v65 row_shr:2 row_mask:0xf bank_mask:0xf
	v_mov_b32_dpp v198, v58 row_shr:1 row_mask:0xf bank_mask:0xf
	v_mov_b32_dpp v200, v58 row_shr:2 row_mask:0xf bank_mask:0xf
	v_mov_b32_dpp v199, v59 row_shr:1 row_mask:0xf bank_mask:0xf
	v_mov_b32_dpp v201, v59 row_shr:2 row_mask:0xf bank_mask:0xf
	v_mov_b32_dpp v202, v60 row_shr:1 row_mask:0xf bank_mask:0xf
	v_mov_b32_dpp v204, v60 row_shr:2 row_mask:0xf bank_mask:0xf
	v_mov_b32_dpp v203, v61 row_shr:1 row_mask:0xf bank_mask:0xf
	v_mov_b32_dpp v205, v61 row_shr:2 row_mask:0xf bank_mask:0xf
	s_and_saveexec_b64 s[56:57], s[42:43]
	s_xor_b64 s[56:57], exec, s[56:57]
	s_cbranch_execz .LBB0_363
	v_pk_fma_f32 v[204:205], v[132:133], v[204:205], v[144:145]
	v_pk_fma_f32 v[200:201], v[130:131], v[200:201], v[142:143]
	v_pk_fma_f32 v[202:203], v[136:137], v[202:203], v[204:205]
	v_pk_fma_f32 v[198:199], v[134:135], v[198:199], v[200:201]
	v_pk_fma_f32 v[202:203], v[60:61], v[140:141], v[202:203]
	v_pk_fma_f32 v[198:199], v[58:59], v[138:139], v[198:199]
	v_mul_f32_e32 v197, 0xbfb8aa3b, v202
	v_mul_f32_e32 v204, 0xbfb8aa3b, v203
	v_exp_f32_e32 v197, v197
	v_exp_f32_e32 v204, v204
	v_pk_fma_f32 v[176:177], v[148:149], v[176:177], v[160:161]
	v_pk_fma_f32 v[172:173], v[146:147], v[172:173], v[158:159]
	v_add_f32_e32 v197, 1.0, v197
	v_add_f32_e32 v205, 1.0, v204
	v_rcp_f32_e32 v204, v197
	v_rcp_f32_e32 v205, v205
	v_mul_f32_e32 v197, 0xbfb8aa3b, v198
	v_exp_f32_e32 v197, v197
	v_pk_fma_f32 v[174:175], v[152:153], v[174:175], v[176:177]
	v_pk_mul_f32 v[200:201], v[202:203], v[204:205]
	v_mul_f32_e32 v202, 0xbfb8aa3b, v199
	v_exp_f32_e32 v203, v202
	v_add_f32_e32 v197, 1.0, v197
	v_pk_fma_f32 v[174:175], v[64:65], v[156:157], v[174:175]
	v_pk_fma_f32 v[170:171], v[150:151], v[170:171], v[172:173]
	v_rcp_f32_e32 v202, v197
	v_add_f32_e32 v197, 1.0, v203
	v_mul_f32_e32 v176, 0xbfb8aa3b, v174
	v_pk_fma_f32 v[170:171], v[62:63], v[154:155], v[170:171]
	v_rcp_f32_e32 v203, v197
	v_exp_f32_e32 v197, v176
	v_mul_f32_e32 v176, 0xbfb8aa3b, v175
	v_mul_f32_e32 v172, 0xbfb8aa3b, v170
	v_mul_f32_e32 v173, 0xbfb8aa3b, v171
	v_exp_f32_e32 v204, v176
	v_exp_f32_e32 v172, v172
	v_exp_f32_e32 v173, v173
	v_add_f32_e32 v197, 1.0, v197
	v_pk_mul_f32 v[176:177], v[198:199], v[202:203]
	v_rcp_f32_e32 v198, v197
	v_add_f32_e32 v197, 1.0, v204
	v_add_f32_e32 v172, 1.0, v172
	v_add_f32_e32 v173, 1.0, v173
	v_rcp_f32_e32 v199, v197
	v_rcp_f32_e32 v172, v172
	v_rcp_f32_e32 v173, v173
	v_pk_mul_f32 v[200:201], v[44:45], v[200:201]
	v_pk_mul_f32 v[174:175], v[174:175], v[198:199]
	v_pk_mul_f32 v[176:177], v[42:43], v[176:177]
	v_pk_mul_f32 v[170:171], v[170:171], v[172:173]
	v_pk_mul_f32 v[174:175], v[48:49], v[174:175]
	v_pk_mul_f32 v[170:171], v[46:47], v[170:171]
	v_cvt_pk_bf16_f32 v172, v176, v177
	v_cvt_pk_bf16_f32 v170, v170, v171
	v_cvt_pk_bf16_f32 v171, v174, v175
	v_mov_b64_e32 v[174:175], s[24:25]
	v_mad_i64_i32 v[174:175], s[68:69], v0, s15, v[174:175]
	v_cvt_pk_bf16_f32 v173, v200, v201
	v_lshl_add_u64 v[174:175], v[162:163], 1, v[174:175]
	global_store_dwordx4 v[174:175], v[170:173], off nt
.LBB0_363:
	s_andn2_saveexec_b64 s[56:57], s[56:57]
	s_cbranch_execz .LBB0_365
	v_ashrrev_i32_e32 v0, 5, v0
	v_lshl_or_b32 v0, v0, 1, v188
	v_mad_i64_i32 v[170:171], s[68:69], v0, s70, v[166:167]
	v_mad_i64_i32 v[172:173], s[68:69], v0, s70, v[168:169]
	global_store_dwordx4 v[170:171], v[62:65], off nt
	global_store_dwordx4 v[170:171], v[58:61], off offset:16 nt
	global_store_dwordx4 v[172:173], v[46:49], off nt
	global_store_dwordx4 v[172:173], v[42:45], off offset:16 nt
.LBB0_365:
	s_or_b64 exec, exec, s[56:57]
	v_mov_b32_e32 v172, v1
	v_mov_b32_e32 v173, v1
	v_mov_b32_e32 v170, v1
	v_mov_b32_dpp v172, v62 row_ror:2 row_mask:0xf bank_mask:0xf
	v_mov_b32_e32 v171, v1
	v_mov_b32_dpp v173, v63 row_ror:2 row_mask:0xf bank_mask:0xf
	v_mov_b32_dpp v170, v62 row_ror:1 row_mask:0xf bank_mask:0xf
	v_mov_b32_dpp v172, v54 row_shr:2 row_mask:0xf bank_mask:0xf
	v_mov_b32_dpp v171, v63 row_ror:1 row_mask:0xf bank_mask:0xf
	v_mov_b32_dpp v173, v55 row_shr:2 row_mask:0xf bank_mask:0xf
	v_mov_b32_dpp v170, v54 row_shr:1 row_mask:0xf bank_mask:0xf
	v_mov_b32_dpp v171, v55 row_shr:1 row_mask:0xf bank_mask:0xf
	v_pk_fma_f32 v[172:173], v[146:147], v[172:173], v[158:159]
	v_mov_b32_e32 v174, v1
	v_pk_fma_f32 v[170:171], v[150:151], v[170:171], v[172:173]
	v_mov_b32_e32 v175, v1
	v_pk_fma_f32 v[170:171], v[54:55], v[154:155], v[170:171]
	v_mov_b32_dpp v174, v64 row_ror:2 row_mask:0xf bank_mask:0xf
	v_mul_f32_e32 v172, 0xbfb8aa3b, v170
	v_mul_f32_e32 v173, 0xbfb8aa3b, v171
	v_exp_f32_e32 v172, v172
	v_exp_f32_e32 v173, v173
	v_mov_b32_dpp v175, v65 row_ror:2 row_mask:0xf bank_mask:0xf
	v_mov_b32_dpp v174, v56 row_shr:2 row_mask:0xf bank_mask:0xf
	v_add_f32_e32 v172, 1.0, v172
	v_add_f32_e32 v173, 1.0, v173
	v_rcp_f32_e32 v172, v172
	v_rcp_f32_e32 v173, v173
	v_mov_b32_dpp v175, v57 row_shr:2 row_mask:0xf bank_mask:0xf
	v_pk_fma_f32 v[174:175], v[148:149], v[174:175], v[160:161]
	v_mov_b32_e32 v176, v1
	v_pk_mul_f32 v[170:171], v[170:171], v[172:173]
	v_mov_b32_e32 v172, v1
	v_mov_b32_e32 v173, v1
	v_mov_b32_e32 v177, v1
	v_mov_b32_dpp v172, v64 row_ror:1 row_mask:0xf bank_mask:0xf
	v_mov_b32_dpp v173, v65 row_ror:1 row_mask:0xf bank_mask:0xf
	v_mov_b32_dpp v176, v58 row_ror:2 row_mask:0xf bank_mask:0xf
	v_mov_b32_dpp v172, v56 row_shr:1 row_mask:0xf bank_mask:0xf
	v_mov_b32_dpp v173, v57 row_shr:1 row_mask:0xf bank_mask:0xf
	v_pk_fma_f32 v[172:173], v[152:153], v[172:173], v[174:175]
	v_mov_b32_dpp v177, v59 row_ror:2 row_mask:0xf bank_mask:0xf
	v_pk_fma_f32 v[172:173], v[56:57], v[156:157], v[172:173]
	v_mov_b32_dpp v176, v50 row_shr:2 row_mask:0xf bank_mask:0xf
	v_mul_f32_e32 v174, 0xbfb8aa3b, v172
	v_mul_f32_e32 v175, 0xbfb8aa3b, v173
	v_exp_f32_e32 v174, v174
	v_exp_f32_e32 v175, v175
	v_mov_b32_dpp v177, v51 row_shr:2 row_mask:0xf bank_mask:0xf
	v_pk_fma_f32 v[176:177], v[130:131], v[176:177], v[142:143]
	v_add_f32_e32 v174, 1.0, v174
	v_add_f32_e32 v175, 1.0, v175
	v_rcp_f32_e32 v174, v174
	v_rcp_f32_e32 v175, v175
	v_mov_b32_e32 v198, v1
	v_mov_b32_e32 v199, v1
	v_pk_mul_f32 v[170:171], v[30:31], v[170:171]
	v_pk_mul_f32 v[172:173], v[172:173], v[174:175]
	v_mov_b32_e32 v174, v1
	v_mov_b32_e32 v175, v1
	v_mov_b32_dpp v198, v60 row_ror:2 row_mask:0xf bank_mask:0xf
	v_mov_b32_dpp v174, v58 row_ror:1 row_mask:0xf bank_mask:0xf
	v_mov_b32_dpp v175, v59 row_ror:1 row_mask:0xf bank_mask:0xf
	v_mov_b32_dpp v199, v61 row_ror:2 row_mask:0xf bank_mask:0xf
	v_mov_b32_dpp v174, v50 row_shr:1 row_mask:0xf bank_mask:0xf
	v_mov_b32_dpp v175, v51 row_shr:1 row_mask:0xf bank_mask:0xf
	v_pk_fma_f32 v[174:175], v[134:135], v[174:175], v[176:177]
	v_mov_b32_dpp v198, v52 row_shr:2 row_mask:0xf bank_mask:0xf
	v_pk_fma_f32 v[174:175], v[50:51], v[138:139], v[174:175]
	v_mov_b32_dpp v199, v53 row_shr:2 row_mask:0xf bank_mask:0xf
	v_mul_f32_e32 v176, 0xbfb8aa3b, v174
	v_mul_f32_e32 v177, 0xbfb8aa3b, v175
	v_exp_f32_e32 v176, v176
	v_exp_f32_e32 v177, v177
	v_pk_fma_f32 v[198:199], v[132:133], v[198:199], v[144:145]
	v_pk_mul_f32 v[172:173], v[32:33], v[172:173]
	v_add_f32_e32 v176, 1.0, v176
	v_add_f32_e32 v177, 1.0, v177
	v_rcp_f32_e32 v176, v176
	v_rcp_f32_e32 v177, v177
	v_add_u32_e32 v0, 0x90, v196
	v_cvt_pk_bf16_f32 v170, v170, v171
	v_cvt_pk_bf16_f32 v171, v172, v173
	v_pk_mul_f32 v[174:175], v[174:175], v[176:177]
	v_mov_b32_e32 v176, v1
	v_mov_b32_e32 v177, v1
	v_pk_mul_f32 v[174:175], v[26:27], v[174:175]
	v_mov_b32_dpp v176, v60 row_ror:1 row_mask:0xf bank_mask:0xf
	v_mov_b32_dpp v177, v61 row_ror:1 row_mask:0xf bank_mask:0xf
	v_cvt_pk_bf16_f32 v172, v174, v175
	v_mov_b32_dpp v176, v52 row_shr:1 row_mask:0xf bank_mask:0xf
	v_mov_b32_dpp v177, v53 row_shr:1 row_mask:0xf bank_mask:0xf
	v_pk_fma_f32 v[176:177], v[136:137], v[176:177], v[198:199]
	v_mov_b64_e32 v[174:175], s[24:25]
	v_pk_fma_f32 v[176:177], v[52:53], v[140:141], v[176:177]
	v_mad_i64_i32 v[174:175], s[56:57], v0, s15, v[174:175]
	v_mul_f32_e32 v197, 0xbfb8aa3b, v176
	v_exp_f32_e32 v197, v197
	v_lshl_add_u64 v[174:175], v[162:163], 1, v[174:175]
	v_add_f32_e32 v197, 1.0, v197
	v_rcp_f32_e32 v198, v197
	v_mul_f32_e32 v197, 0xbfb8aa3b, v177
	v_exp_f32_e32 v197, v197
	s_nop 0
	v_add_f32_e32 v197, 1.0, v197
	v_rcp_f32_e32 v199, v197
	s_nop 0
	v_pk_mul_f32 v[176:177], v[176:177], v[198:199]
	s_nop 0
	v_pk_mul_f32 v[176:177], v[28:29], v[176:177]
	s_nop 0
	v_cvt_pk_bf16_f32 v173, v176, v177
	global_store_dwordx4 v[174:175], v[170:173], off nt
	s_and_saveexec_b64 s[56:57], s[50:51]
	s_cbranch_execz .LBB0_367
	v_ashrrev_i32_e32 v0, 5, v0
	v_lshl_add_u32 v0, v0, 1, v190
	v_mad_i64_i32 v[170:171], s[50:51], v0, s70, v[164:165]
	global_store_dwordx4 v[170:171], v[54:57], off nt
	global_store_dwordx4 v[170:171], v[50:53], off offset:16 nt
.LBB0_367:
	s_or_b64 exec, exec, s[56:57]
	v_cndmask_b32_e64 v171, v54, 0, s[48:49]
	v_mov_b32_e32 v170, v1
	v_mov_b32_e32 v172, v1
	v_cndmask_b32_e64 v174, v55, 0, s[48:49]
	v_mov_b32_dpp v170, v171 row_ror:1 row_mask:0xf bank_mask:0xf
	v_mov_b32_dpp v172, v171 row_ror:2 row_mask:0xf bank_mask:0xf
	v_mov_b32_e32 v171, v1
	v_mov_b32_e32 v173, v1
	v_cndmask_b32_e64 v175, v56, 0, s[48:49]
	v_mov_b32_dpp v171, v174 row_ror:1 row_mask:0xf bank_mask:0xf
	v_mov_b32_dpp v173, v174 row_ror:2 row_mask:0xf bank_mask:0xf
	v_mov_b32_e32 v174, v1
	v_mov_b32_e32 v176, v1
	v_cndmask_b32_e64 v197, v57, 0, s[48:49]
	v_mov_b32_dpp v174, v175 row_ror:1 row_mask:0xf bank_mask:0xf
	v_mov_b32_dpp v176, v175 row_ror:2 row_mask:0xf bank_mask:0xf
	v_mov_b32_e32 v175, v1
	v_mov_b32_e32 v177, v1
	v_mov_b32_e32 v198, v1
	v_mov_b32_dpp v175, v197 row_ror:1 row_mask:0xf bank_mask:0xf
	v_mov_b32_dpp v177, v197 row_ror:2 row_mask:0xf bank_mask:0xf
	v_cndmask_b32_e64 v197, v50, 0, s[48:49]
	v_mov_b32_e32 v200, v1
	v_mov_b32_e32 v199, v1
	v_mov_b32_dpp v198, v197 row_ror:1 row_mask:0xf bank_mask:0xf
	v_mov_b32_dpp v200, v197 row_ror:2 row_mask:0xf bank_mask:0xf
	v_cndmask_b32_e64 v197, v51, 0, s[48:49]
	v_mov_b32_e32 v201, v1
	v_mov_b32_e32 v202, v1
	v_mov_b32_dpp v199, v197 row_ror:1 row_mask:0xf bank_mask:0xf
	v_mov_b32_dpp v201, v197 row_ror:2 row_mask:0xf bank_mask:0xf
	v_cndmask_b32_e64 v197, v52, 0, s[48:49]
	v_mov_b32_e32 v204, v1
	v_mov_b32_e32 v203, v1
	v_mov_b32_dpp v202, v197 row_ror:1 row_mask:0xf bank_mask:0xf
	v_mov_b32_dpp v204, v197 row_ror:2 row_mask:0xf bank_mask:0xf
	v_cndmask_b32_e64 v197, v53, 0, s[48:49]
	v_mov_b32_e32 v205, v1
	v_add_u32_e32 v0, 0xa0, v196
	v_mov_b32_dpp v203, v197 row_ror:1 row_mask:0xf bank_mask:0xf
	v_mov_b32_dpp v205, v197 row_ror:2 row_mask:0xf bank_mask:0xf
	v_mov_b32_dpp v170, v38 row_shr:1 row_mask:0xf bank_mask:0xf
	v_mov_b32_dpp v172, v38 row_shr:2 row_mask:0xf bank_mask:0xf
	v_mov_b32_dpp v171, v39 row_shr:1 row_mask:0xf bank_mask:0xf
	v_mov_b32_dpp v173, v39 row_shr:2 row_mask:0xf bank_mask:0xf
	v_mov_b32_dpp v174, v40 row_shr:1 row_mask:0xf bank_mask:0xf
	v_mov_b32_dpp v176, v40 row_shr:2 row_mask:0xf bank_mask:0xf
	v_mov_b32_dpp v175, v41 row_shr:1 row_mask:0xf bank_mask:0xf
	v_mov_b32_dpp v177, v41 row_shr:2 row_mask:0xf bank_mask:0xf
	v_mov_b32_dpp v198, v34 row_shr:1 row_mask:0xf bank_mask:0xf
	v_mov_b32_dpp v200, v34 row_shr:2 row_mask:0xf bank_mask:0xf
	v_mov_b32_dpp v199, v35 row_shr:1 row_mask:0xf bank_mask:0xf
	v_mov_b32_dpp v201, v35 row_shr:2 row_mask:0xf bank_mask:0xf
	v_mov_b32_dpp v202, v36 row_shr:1 row_mask:0xf bank_mask:0xf
	v_mov_b32_dpp v204, v36 row_shr:2 row_mask:0xf bank_mask:0xf
	v_mov_b32_dpp v203, v37 row_shr:1 row_mask:0xf bank_mask:0xf
	v_mov_b32_dpp v205, v37 row_shr:2 row_mask:0xf bank_mask:0xf
	s_and_saveexec_b64 s[48:49], s[54:55]
	s_xor_b64 s[48:49], exec, s[48:49]
	s_cbranch_execz .LBB0_369
	v_pk_fma_f32 v[166:167], v[132:133], v[204:205], v[144:145]
	v_pk_fma_f32 v[200:201], v[130:131], v[200:201], v[142:143]
	v_pk_fma_f32 v[166:167], v[136:137], v[202:203], v[166:167]
	v_pk_fma_f32 v[198:199], v[134:135], v[198:199], v[200:201]
	v_pk_fma_f32 v[166:167], v[36:37], v[140:141], v[166:167]
	v_pk_fma_f32 v[176:177], v[148:149], v[176:177], v[160:161]
	v_mul_f32_e32 v168, 0xbfb8aa3b, v166
	v_mul_f32_e32 v169, 0xbfb8aa3b, v167
	v_exp_f32_e32 v168, v168
	v_exp_f32_e32 v169, v169
	v_pk_fma_f32 v[174:175], v[152:153], v[174:175], v[176:177]
	v_pk_fma_f32 v[172:173], v[146:147], v[172:173], v[158:159]
	v_add_f32_e32 v168, 1.0, v168
	v_add_f32_e32 v169, 1.0, v169
	v_rcp_f32_e32 v168, v168
	v_rcp_f32_e32 v169, v169
	v_pk_fma_f32 v[174:175], v[40:41], v[156:157], v[174:175]
	v_pk_fma_f32 v[170:171], v[150:151], v[170:171], v[172:173]
	v_mul_f32_e32 v176, 0xbfb8aa3b, v174
	v_pk_mul_f32 v[166:167], v[166:167], v[168:169]
	v_pk_fma_f32 v[168:169], v[34:35], v[138:139], v[198:199]
	v_mul_f32_e32 v177, 0xbfb8aa3b, v175
	v_mul_f32_e32 v197, 0xbfb8aa3b, v168
	v_mul_f32_e32 v198, 0xbfb8aa3b, v169
	v_exp_f32_e32 v197, v197
	v_exp_f32_e32 v200, v198
	v_pk_mul_f32 v[198:199], v[12:13], v[166:167]
	v_pk_fma_f32 v[170:171], v[38:39], v[154:155], v[170:171]
	v_add_f32_e32 v166, 1.0, v197
	v_add_f32_e32 v167, 1.0, v200
	v_rcp_f32_e32 v166, v166
	v_rcp_f32_e32 v167, v167
	v_exp_f32_e32 v176, v176
	v_exp_f32_e32 v177, v177
	v_mul_f32_e32 v172, 0xbfb8aa3b, v170
	v_mul_f32_e32 v173, 0xbfb8aa3b, v171
	v_exp_f32_e32 v172, v172
	v_exp_f32_e32 v173, v173
	v_pk_mul_f32 v[166:167], v[168:169], v[166:167]
	v_add_f32_e32 v168, 1.0, v176
	v_add_f32_e32 v169, 1.0, v177
	v_rcp_f32_e32 v168, v168
	v_rcp_f32_e32 v169, v169
	v_add_f32_e32 v172, 1.0, v172
	v_add_f32_e32 v173, 1.0, v173
	v_rcp_f32_e32 v172, v172
	v_rcp_f32_e32 v173, v173
	v_pk_mul_f32 v[176:177], v[10:11], v[166:167]
	v_pk_mul_f32 v[166:167], v[174:175], v[168:169]
	s_nop 0
	v_pk_mul_f32 v[168:169], v[16:17], v[166:167]
	v_pk_mul_f32 v[166:167], v[170:171], v[172:173]
	v_mov_b64_e32 v[170:171], s[24:25]
	v_pk_mul_f32 v[166:167], v[14:15], v[166:167]
	v_mad_i64_i32 v[170:171], s[50:51], v0, s15, v[170:171]
	v_cvt_pk_bf16_f32 v166, v166, v167
	v_cvt_pk_bf16_f32 v167, v168, v169
	v_cvt_pk_bf16_f32 v168, v176, v177
	v_cvt_pk_bf16_f32 v169, v198, v199
	v_lshl_add_u64 v[170:171], v[162:163], 1, v[170:171]
	global_store_dwordx4 v[170:171], v[166:169], off nt
.LBB0_369:
	s_andn2_saveexec_b64 s[48:49], s[48:49]
	s_cbranch_execz .LBB0_371
	v_ashrrev_i32_e32 v0, 5, v0
	v_lshl_or_b32 v0, v0, 1, v188
	v_mad_i64_i32 v[166:167], s[50:51], v0, s70, v[166:167]
	v_mad_i64_i32 v[168:169], s[50:51], v0, s70, v[168:169]
	global_store_dwordx4 v[166:167], v[38:41], off nt
	global_store_dwordx4 v[166:167], v[34:37], off offset:16 nt
	global_store_dwordx4 v[168:169], v[14:17], off nt
	global_store_dwordx4 v[168:169], v[10:13], off offset:16 nt
.LBB0_371:
	s_or_b64 exec, exec, s[48:49]
	v_mov_b32_e32 v168, v1
	v_mov_b32_e32 v169, v1
	v_mov_b32_e32 v166, v1
	v_mov_b32_dpp v168, v38 row_ror:2 row_mask:0xf bank_mask:0xf
	v_mov_b32_e32 v167, v1
	v_mov_b32_dpp v169, v39 row_ror:2 row_mask:0xf bank_mask:0xf
	v_mov_b32_dpp v166, v38 row_ror:1 row_mask:0xf bank_mask:0xf
	v_mov_b32_dpp v168, v22 row_shr:2 row_mask:0xf bank_mask:0xf
	v_mov_b32_dpp v167, v39 row_ror:1 row_mask:0xf bank_mask:0xf
	v_mov_b32_dpp v169, v23 row_shr:2 row_mask:0xf bank_mask:0xf
	v_mov_b32_dpp v166, v22 row_shr:1 row_mask:0xf bank_mask:0xf
	v_mov_b32_dpp v167, v23 row_shr:1 row_mask:0xf bank_mask:0xf
	v_pk_fma_f32 v[146:147], v[146:147], v[168:169], v[158:159]
	s_nop 0
	v_pk_fma_f32 v[146:147], v[150:151], v[166:167], v[146:147]
	s_nop 0
	v_pk_fma_f32 v[146:147], v[22:23], v[154:155], v[146:147]
	v_mov_b32_e32 v154, v1
	v_mul_f32_e32 v0, 0xbfb8aa3b, v146
	v_exp_f32_e32 v0, v0
	v_mul_f32_e32 v150, 0xbfb8aa3b, v147
	v_exp_f32_e32 v151, v150
	v_mov_b32_e32 v155, v1
	v_add_f32_e32 v0, 1.0, v0
	v_rcp_f32_e32 v150, v0
	v_add_f32_e32 v0, 1.0, v151
	v_rcp_f32_e32 v151, v0
	v_mov_b32_dpp v154, v40 row_ror:2 row_mask:0xf bank_mask:0xf
	v_mov_b32_dpp v155, v41 row_ror:2 row_mask:0xf bank_mask:0xf
	v_add_u32_e32 v0, 0xb0, v196
	v_pk_mul_f32 v[146:147], v[146:147], v[150:151]
	v_mov_b32_e32 v150, v1
	v_mov_b32_e32 v151, v1
	v_mov_b32_dpp v154, v24 row_shr:2 row_mask:0xf bank_mask:0xf
	v_mov_b32_dpp v150, v40 row_ror:1 row_mask:0xf bank_mask:0xf
	v_mov_b32_dpp v151, v41 row_ror:1 row_mask:0xf bank_mask:0xf
	v_mov_b32_dpp v155, v25 row_shr:2 row_mask:0xf bank_mask:0xf
	v_mov_b32_dpp v150, v24 row_shr:1 row_mask:0xf bank_mask:0xf
	v_mov_b32_dpp v151, v25 row_shr:1 row_mask:0xf bank_mask:0xf
	v_pk_fma_f32 v[148:149], v[148:149], v[154:155], v[160:161]
	v_mov_b32_e32 v154, v1
	v_pk_fma_f32 v[148:149], v[152:153], v[150:151], v[148:149]
	v_mov_b32_e32 v155, v1
	v_pk_fma_f32 v[148:149], v[24:25], v[156:157], v[148:149]
	v_mov_b32_e32 v152, v1
	v_mul_f32_e32 v150, 0xbfb8aa3b, v148
	v_mul_f32_e32 v151, 0xbfb8aa3b, v149
	v_exp_f32_e32 v150, v150
	v_exp_f32_e32 v151, v151
	v_mov_b32_dpp v154, v34 row_ror:2 row_mask:0xf bank_mask:0xf
	v_mov_b32_e32 v153, v1
	v_mov_b32_dpp v155, v35 row_ror:2 row_mask:0xf bank_mask:0xf
	v_mov_b32_dpp v152, v34 row_ror:1 row_mask:0xf bank_mask:0xf
	v_mov_b32_dpp v154, v18 row_shr:2 row_mask:0xf bank_mask:0xf
	v_mov_b32_dpp v153, v35 row_ror:1 row_mask:0xf bank_mask:0xf
	v_mov_b32_dpp v155, v19 row_shr:2 row_mask:0xf bank_mask:0xf
	v_add_f32_e32 v150, 1.0, v150
	v_add_f32_e32 v151, 1.0, v151
	v_mov_b32_dpp v152, v18 row_shr:1 row_mask:0xf bank_mask:0xf
	v_mov_b32_dpp v153, v19 row_shr:1 row_mask:0xf bank_mask:0xf
	v_pk_fma_f32 v[130:131], v[130:131], v[154:155], v[142:143]
	v_rcp_f32_e32 v150, v150
	v_rcp_f32_e32 v151, v151
	v_pk_fma_f32 v[130:131], v[134:135], v[152:153], v[130:131]
	v_mov_b32_e32 v142, v1
	v_pk_fma_f32 v[130:131], v[18:19], v[138:139], v[130:131]
	v_mov_b32_e32 v143, v1
	v_mul_f32_e32 v134, 0xbfb8aa3b, v130
	v_exp_f32_e32 v138, v134
	v_mul_f32_e32 v134, 0xbfb8aa3b, v131
	v_exp_f32_e32 v139, v134
	v_pk_mul_f32 v[134:135], v[148:149], v[150:151]
	v_mov_b32_e32 v148, v1
	v_mov_b32_e32 v149, v1
	v_mov_b32_dpp v142, v36 row_ror:1 row_mask:0xf bank_mask:0xf
	v_mov_b32_dpp v148, v36 row_ror:2 row_mask:0xf bank_mask:0xf
	v_mov_b32_dpp v149, v37 row_ror:2 row_mask:0xf bank_mask:0xf
	v_mov_b32_dpp v143, v37 row_ror:1 row_mask:0xf bank_mask:0xf
	v_mov_b32_dpp v148, v20 row_shr:2 row_mask:0xf bank_mask:0xf
	v_mov_b32_dpp v149, v21 row_shr:2 row_mask:0xf bank_mask:0xf
	v_mov_b32_dpp v142, v20 row_shr:1 row_mask:0xf bank_mask:0xf
	v_mov_b32_dpp v143, v21 row_shr:1 row_mask:0xf bank_mask:0xf
	v_pk_fma_f32 v[132:133], v[132:133], v[148:149], v[144:145]
	v_add_f32_e32 v138, 1.0, v138
	v_pk_fma_f32 v[132:133], v[136:137], v[142:143], v[132:133]
	v_add_f32_e32 v139, 1.0, v139
	v_pk_fma_f32 v[132:133], v[20:21], v[140:141], v[132:133]
	v_rcp_f32_e32 v138, v138
	v_mul_f32_e32 v136, 0xbfb8aa3b, v132
	v_mul_f32_e32 v137, 0xbfb8aa3b, v133
	v_exp_f32_e32 v136, v136
	v_exp_f32_e32 v137, v137
	v_rcp_f32_e32 v139, v139
	v_pk_mul_f32 v[134:135], v[8:9], v[134:135]
	v_add_f32_e32 v136, 1.0, v136
	v_add_f32_e32 v137, 1.0, v137
	v_rcp_f32_e32 v136, v136
	v_rcp_f32_e32 v137, v137
	v_pk_mul_f32 v[130:131], v[130:131], v[138:139]
	v_pk_mul_f32 v[146:147], v[6:7], v[146:147]
	v_pk_mul_f32 v[138:139], v[2:3], v[130:131]
	v_pk_mul_f32 v[130:131], v[132:133], v[136:137]
	v_cvt_pk_bf16_f32 v132, v138, v139
	v_pk_mul_f32 v[136:137], v[4:5], v[130:131]
	v_cvt_pk_bf16_f32 v131, v134, v135
	v_mov_b64_e32 v[134:135], s[24:25]
	v_mad_i64_i32 v[134:135], s[48:49], v0, s15, v[134:135]
	v_cvt_pk_bf16_f32 v130, v146, v147
	v_cvt_pk_bf16_f32 v133, v136, v137
	v_lshl_add_u64 v[134:135], v[162:163], 1, v[134:135]
	global_store_dwordx4 v[134:135], v[130:133], off nt
	s_and_saveexec_b64 s[48:49], s[44:45]
	s_cbranch_execz .LBB0_373
	v_ashrrev_i32_e32 v0, 5, v0
	v_lshl_add_u32 v0, v0, 1, v190
	v_mad_i64_i32 v[130:131], s[50:51], v0, s70, v[164:165]
	global_store_dwordx4 v[130:131], v[22:25], off nt
	global_store_dwordx4 v[130:131], v[18:21], off offset:16 nt

.LBB0_374:
	s_and_b64 vcc, exec, s[48:49]
	s_cbranch_vccz .LBB0_387
	v_lshl_or_b32 v202, s23, 8, v225
	s_cmp_lt_i32 s88, 0
	s_mov_b64 s[48:49], -1
	v_ashrrev_i32_e32 v203, 31, v202
	v_add_u32_e32 v204, 0xffffe000, v196
	v_add_u32_e32 v200, 0xffffe010, v196
	v_add_u32_e32 v198, 0xffffe020, v196
	s_cbranch_scc0 .LBB0_385
	s_cmp_lt_i32 s55, 32
	s_cbranch_scc0 .Lrk_store
	s_movk_i32 s15, 0x2000
	v_ashrrev_i32_e32 v197, 31, v196
	v_cmp_gt_i32_e32 vcc, s15, v196
	v_mov_b32_e32 v0, s77
	v_mov_b32_e32 v134, s19
	v_cndmask_b32_e32 v131, 0, v197, vcc
	v_cndmask_b32_e32 v130, v204, v196, vcc
	v_mov_b32_e32 v135, s76
	v_mov_b32_e32 v136, s18
	v_cndmask_b32_e32 v133, v0, v134, vcc
	v_cndmask_b32_e32 v132, v135, v136, vcc
	v_lshlrev_b64 v[130:131], 13, v[130:131]
	v_lshl_add_u64 v[130:131], v[132:133], 0, v[130:131]
	v_lshlrev_b64 v[206:207], 2, v[202:203]
	v_or_b32_e32 v212, 16, v196
	v_lshl_add_u64 v[130:131], v[130:131], 0, v[206:207]
	v_ashrrev_i32_e32 v213, 31, v212
	v_cmp_gt_i32_e32 vcc, s15, v212
	global_load_dwordx4 v[174:177], v[130:131], off
	global_load_dwordx4 v[170:173], v[130:131], off offset:64
	global_load_dwordx4 v[166:169], v[130:131], off offset:512
	global_load_dwordx4 v[162:165], v[130:131], off offset:576
	v_cndmask_b32_e32 v131, 0, v213, vcc
	v_cndmask_b32_e32 v130, v200, v212, vcc
	v_cndmask_b32_e32 v133, v0, v134, vcc
	v_cndmask_b32_e32 v132, v135, v136, vcc
	v_lshlrev_b64 v[130:131], 13, v[130:131]
	v_lshl_add_u64 v[130:131], v[132:133], 0, v[130:131]
	v_or_b32_e32 v210, 32, v196
	v_lshl_add_u64 v[130:131], v[130:131], 0, v[206:207]
	v_ashrrev_i32_e32 v211, 31, v210
	v_cmp_gt_i32_e32 vcc, s15, v210
	global_load_dwordx4 v[158:161], v[130:131], off
	global_load_dwordx4 v[154:157], v[130:131], off offset:64
	global_load_dwordx4 v[150:153], v[130:131], off offset:512
	global_load_dwordx4 v[146:149], v[130:131], off offset:576
	v_cndmask_b32_e32 v131, 0, v211, vcc
	v_cndmask_b32_e32 v130, v198, v210, vcc
	v_cndmask_b32_e32 v133, v0, v134, vcc
	v_cndmask_b32_e32 v132, v135, v136, vcc
	v_lshlrev_b64 v[130:131], 13, v[130:131]
	v_lshl_add_u64 v[130:131], v[132:133], 0, v[130:131]
	v_lshl_add_u64 v[130:131], v[130:131], 0, v[206:207]
	global_load_dwordx4 v[142:145], v[130:131], off
	global_load_dwordx4 v[138:141], v[130:131], off offset:64
	global_load_dwordx4 v[134:137], v[130:131], off offset:512
	s_nop 0
	global_load_dwordx4 v[130:133], v[130:131], off offset:576
	v_or_b32_e32 v214, 48, v196
	s_movk_i32 s15, 0x1fff
	v_cmp_lt_i32_e32 vcc, s15, v214
	s_and_saveexec_b64 s[48:49], vcc
	s_xor_b64 s[48:49], exec, s[48:49]
	v_add_u32_e32 v0, 0xffffe030, v196
	v_lshlrev_b64 v[208:209], 13, v[0:1]
	v_mov_b32_e32 v215, v1
	v_lshl_add_u64 v[216:217], s[76:77], 0, v[208:209]
	v_lshlrev_b64 v[208:209], 13, v[214:215]
	s_andn2_saveexec_b64 s[48:49], s[48:49]
	v_ashrrev_i32_e32 v215, 31, v214
	v_lshlrev_b64 v[208:209], 13, v[214:215]
	v_lshl_add_u64 v[216:217], s[18:19], 0, v[208:209]
	s_or_b64 exec, exec, s[48:49]
	v_lshl_add_u64 v[218:219], v[216:217], 0, v[206:207]
	global_load_dwordx4 v[214:217], v[218:219], off
	global_load_dwordx4 v[232:235], v[218:219], off offset:64
	global_load_dwordx4 v[236:239], v[218:219], off offset:512
	global_load_dwordx4 v[240:243], v[218:219], off offset:576
	v_lshlrev_b64 v[218:219], 13, v[196:197]
	v_lshl_add_u64 v[218:219], s[78:79], 0, v[218:219]
	v_lshl_add_u64 v[218:219], v[218:219], 0, v[206:207]
	s_waitcnt vmcnt(0)
	v_pk_add_f32 v[164:165], v[108:109], v[164:165]
	v_pk_add_f32 v[162:163], v[106:107], v[162:163]
	global_store_dwordx4 v[218:219], v[162:165], off offset:576 nt
	v_pk_add_f32 v[148:149], v[92:93], v[148:149]
	v_pk_add_f32 v[146:147], v[90:91], v[146:147]
	v_lshlrev_b64 v[162:163], 13, v[212:213]
	v_lshl_add_u64 v[162:163], s[78:79], 0, v[162:163]
	v_lshl_add_u64 v[162:163], v[162:163], 0, v[206:207]
	global_store_dwordx4 v[162:163], v[146:149], off offset:576 nt
	v_pk_add_f32 v[132:133], v[76:77], v[132:133]
	v_pk_add_f32 v[130:131], v[74:75], v[130:131]
	v_lshlrev_b64 v[146:147], 13, v[210:211]
	v_lshl_add_u64 v[146:147], s[78:79], 0, v[146:147]
	v_lshl_add_u64 v[146:147], v[146:147], 0, v[206:207]
	v_pk_add_f32 v[136:137], v[80:81], v[136:137]
	v_pk_add_f32 v[134:135], v[78:79], v[134:135]
	global_store_dwordx4 v[146:147], v[130:133], off offset:576 nt
	v_pk_add_f32 v[176:177], v[176:177], v[128:129]
	v_pk_add_f32 v[174:175], v[174:175], v[126:127]
	v_lshl_add_u64 v[130:131], s[78:79], 0, v[208:209]
	v_pk_add_f32 v[172:173], v[172:173], v[124:125]
	v_pk_add_f32 v[170:171], v[170:171], v[122:123]
	v_pk_add_f32 v[168:169], v[112:113], v[168:169]
	v_pk_add_f32 v[166:167], v[110:111], v[166:167]
	v_pk_add_f32 v[160:161], v[160:161], v[120:121]
	v_pk_add_f32 v[158:159], v[158:159], v[118:119]
	v_pk_add_f32 v[156:157], v[156:157], v[116:117]
	v_pk_add_f32 v[154:155], v[154:155], v[114:115]
	v_pk_add_f32 v[152:153], v[96:97], v[152:153]
	v_pk_add_f32 v[150:151], v[94:95], v[150:151]
	v_pk_add_f32 v[144:145], v[144:145], v[104:105]
	v_pk_add_f32 v[142:143], v[142:143], v[102:103]
	v_pk_add_f32 v[140:141], v[140:141], v[100:101]
	v_pk_add_f32 v[138:139], v[138:139], v[98:99]
	global_store_dwordx4 v[146:147], v[134:137], off offset:512 nt
	global_store_dwordx4 v[218:219], v[174:177], off nt
	global_store_dwordx4 v[218:219], v[170:173], off offset:64 nt
	v_lshl_add_u64 v[134:135], v[130:131], 0, v[206:207]
	global_store_dwordx4 v[218:219], v[166:169], off offset:512 nt
	global_store_dwordx4 v[162:163], v[158:161], off nt
	global_store_dwordx4 v[162:163], v[154:157], off offset:64 nt
	global_store_dwordx4 v[162:163], v[150:153], off offset:512 nt
	global_store_dwordx4 v[146:147], v[142:145], off nt
	global_store_dwordx4 v[146:147], v[138:141], off offset:64 nt
	s_movk_i32 s15, 0x1f80
	v_add_u32_e32 v208, 0x80, v196
	v_cmp_gt_i32_e32 vcc, s15, v196
	v_add_u32_e32 v0, 0xffffe080, v196
	v_ashrrev_i32_e32 v209, 31, v208
	v_mov_b32_e32 v150, s19
	v_mov_b32_e32 v151, s76
	v_mov_b32_e32 v152, s18
	v_add_u32_e32 v210, 0x90, v196
	s_movk_i32 s15, 0x1f70
	v_ashrrev_i32_e32 v211, 31, v210
	v_add_u32_e32 v146, 0xffffe090, v196
	v_pk_add_f32 v[132:133], v[88:89], v[216:217]
	v_pk_add_f32 v[130:131], v[86:87], v[214:215]
	global_store_dwordx4 v[134:135], v[130:133], off nt
	v_add_u32_e32 v214, 0xa0, v196
	v_ashrrev_i32_e32 v215, 31, v214
	v_pk_add_f32 v[132:133], v[84:85], v[234:235]
	v_pk_add_f32 v[130:131], v[82:83], v[232:233]
	global_store_dwordx4 v[134:135], v[130:133], off offset:64 nt
	v_add_u32_e32 v216, 0xb0, v196
	s_nop 0
	v_pk_add_f32 v[132:133], v[72:73], v[238:239]
	v_pk_add_f32 v[130:131], v[70:71], v[236:237]
	global_store_dwordx4 v[134:135], v[130:133], off offset:512 nt
	s_nop 1
	v_pk_add_f32 v[132:133], v[68:69], v[242:243]
	v_pk_add_f32 v[130:131], v[66:67], v[240:241]
	global_store_dwordx4 v[134:135], v[130:133], off offset:576 nt
	s_nop 1
	v_cndmask_b32_e32 v130, v0, v208, vcc
	v_mov_b32_e32 v0, s77
	v_cndmask_b32_e32 v131, 0, v209, vcc
	v_cndmask_b32_e32 v133, v0, v150, vcc
	v_cndmask_b32_e32 v132, v151, v152, vcc
	v_cmp_gt_i32_e32 vcc, s15, v196
	v_lshlrev_b64 v[130:131], 13, v[130:131]
	v_lshl_add_u64 v[130:131], v[132:133], 0, v[130:131]
	v_cndmask_b32_e32 v147, 0, v211, vcc
	v_cndmask_b32_e32 v146, v146, v210, vcc
	v_cndmask_b32_e32 v149, v0, v150, vcc
	v_cndmask_b32_e32 v148, v151, v152, vcc
	v_lshlrev_b64 v[146:147], 13, v[146:147]
	v_lshl_add_u64 v[146:147], v[148:149], 0, v[146:147]
	v_lshl_add_u64 v[130:131], v[130:131], 0, v[206:207]
	v_lshl_add_u64 v[146:147], v[146:147], 0, v[206:207]
	s_movk_i32 s15, 0x1f60
	global_load_dwordx4 v[142:145], v[130:131], off
	global_load_dwordx4 v[138:141], v[130:131], off offset:64
	global_load_dwordx4 v[134:137], v[130:131], off offset:512
	s_nop 0
	global_load_dwordx4 v[130:133], v[130:131], off offset:576
	s_nop 0
	global_load_dwordx4 v[174:177], v[146:147], off
	global_load_dwordx4 v[170:173], v[146:147], off offset:64
	global_load_dwordx4 v[162:165], v[146:147], off offset:512
	global_load_dwordx4 v[154:157], v[146:147], off offset:576
	v_cmp_gt_i32_e32 vcc, s15, v196
	v_add_u32_e32 v146, 0xffffe0a0, v196
	s_movk_i32 s15, 0x1f4f
	v_cndmask_b32_e32 v147, 0, v215, vcc
	v_cndmask_b32_e32 v146, v146, v214, vcc
	v_cndmask_b32_e32 v149, v0, v150, vcc
	v_cndmask_b32_e32 v148, v151, v152, vcc
	v_lshlrev_b64 v[146:147], 13, v[146:147]
	v_lshl_add_u64 v[146:147], v[148:149], 0, v[146:147]
	v_lshl_add_u64 v[146:147], v[146:147], 0, v[206:207]
	global_load_dwordx4 v[166:169], v[146:147], off
	global_load_dwordx4 v[158:161], v[146:147], off offset:64
	global_load_dwordx4 v[150:153], v[146:147], off offset:512
	s_nop 0
	global_load_dwordx4 v[146:149], v[146:147], off offset:576
	v_cmp_lt_i32_e32 vcc, s15, v196
	s_and_saveexec_b64 s[48:49], vcc
	s_xor_b64 s[48:49], exec, s[48:49]
	v_add_u32_e32 v0, 0xffffe0b0, v196
	v_lshlrev_b64 v[212:213], 13, v[0:1]
	v_mov_b32_e32 v217, v1
	v_lshl_add_u64 v[218:219], s[76:77], 0, v[212:213]
	v_lshlrev_b64 v[212:213], 13, v[216:217]
	s_andn2_saveexec_b64 s[48:49], s[48:49]
	v_ashrrev_i32_e32 v217, 31, v216
	v_lshlrev_b64 v[212:213], 13, v[216:217]
	v_lshl_add_u64 v[218:219], s[18:19], 0, v[212:213]
	s_or_b64 exec, exec, s[48:49]
	v_lshl_add_u64 v[240:241], v[218:219], 0, v[206:207]
	global_load_dwordx4 v[216:219], v[240:241], off
	global_load_dwordx4 v[232:235], v[240:241], off offset:64
	global_load_dwordx4 v[236:239], v[240:241], off offset:512
	s_nop 0
	global_load_dwordx4 v[240:243], v[240:241], off offset:576
	v_lshlrev_b64 v[208:209], 13, v[208:209]
	v_lshlrev_b64 v[210:211], 13, v[210:211]
	v_lshlrev_b64 v[214:215], 13, v[214:215]
	v_lshl_add_u64 v[208:209], s[78:79], 0, v[208:209]
	s_waitcnt vmcnt(15)
	v_pk_add_f32 v[144:145], v[144:145], v[64:65]
	v_pk_add_f32 v[142:143], v[142:143], v[62:63]
	s_waitcnt vmcnt(12)
	v_pk_add_f32 v[132:133], v[44:45], v[132:133]
	v_pk_add_f32 v[130:131], v[42:43], v[130:131]
	v_lshl_add_u64 v[212:213], s[78:79], 0, v[212:213]
	v_lshl_add_u64 v[210:211], s[78:79], 0, v[210:211]
	v_lshl_add_u64 v[214:215], s[78:79], 0, v[214:215]
	v_lshl_add_u64 v[208:209], v[208:209], 0, v[206:207]
	v_pk_add_f32 v[140:141], v[140:141], v[60:61]
	v_pk_add_f32 v[138:139], v[138:139], v[58:59]
	v_pk_add_f32 v[136:137], v[48:49], v[136:137]
	v_pk_add_f32 v[134:135], v[46:47], v[134:135]
	s_waitcnt vmcnt(11)
	v_pk_add_f32 v[176:177], v[176:177], v[56:57]
	v_pk_add_f32 v[174:175], v[174:175], v[54:55]
	s_waitcnt vmcnt(10)
	v_pk_add_f32 v[172:173], v[172:173], v[52:53]
	v_pk_add_f32 v[170:171], v[170:171], v[50:51]
	s_waitcnt vmcnt(9)
	v_pk_add_f32 v[164:165], v[32:33], v[164:165]
	v_pk_add_f32 v[162:163], v[30:31], v[162:163]
	s_waitcnt vmcnt(8)
	v_pk_add_f32 v[156:157], v[28:29], v[156:157]
	v_pk_add_f32 v[154:155], v[26:27], v[154:155]
	s_waitcnt vmcnt(7)
	v_pk_add_f32 v[168:169], v[168:169], v[40:41]
	v_pk_add_f32 v[166:167], v[166:167], v[38:39]
	s_waitcnt vmcnt(6)
	v_pk_add_f32 v[160:161], v[160:161], v[36:37]
	v_pk_add_f32 v[158:159], v[158:159], v[34:35]
	s_waitcnt vmcnt(5)
	v_pk_add_f32 v[152:153], v[16:17], v[152:153]
	v_pk_add_f32 v[150:151], v[14:15], v[150:151]
	s_waitcnt vmcnt(4)
	v_pk_add_f32 v[148:149], v[12:13], v[148:149]
	v_pk_add_f32 v[146:147], v[10:11], v[146:147]
	v_lshl_add_u64 v[212:213], v[212:213], 0, v[206:207]
	v_lshl_add_u64 v[210:211], v[210:211], 0, v[206:207]
	v_lshl_add_u64 v[206:207], v[214:215], 0, v[206:207]
	global_store_dwordx4 v[208:209], v[142:145], off nt
	global_store_dwordx4 v[208:209], v[138:141], off offset:64 nt
	global_store_dwordx4 v[208:209], v[134:137], off offset:512 nt
	global_store_dwordx4 v[208:209], v[130:133], off offset:576 nt
	global_store_dwordx4 v[210:211], v[174:177], off nt
	global_store_dwordx4 v[210:211], v[170:173], off offset:64 nt
	global_store_dwordx4 v[210:211], v[162:165], off offset:512 nt
	global_store_dwordx4 v[210:211], v[154:157], off offset:576 nt
	global_store_dwordx4 v[206:207], v[166:169], off nt
	global_store_dwordx4 v[206:207], v[158:161], off offset:64 nt
	global_store_dwordx4 v[206:207], v[150:153], off offset:512 nt
	global_store_dwordx4 v[206:207], v[146:149], off offset:576 nt
	s_mov_b64 s[48:49], 0
	s_waitcnt vmcnt(15)
	v_pk_add_f32 v[132:133], v[24:25], v[218:219]
	v_pk_add_f32 v[130:131], v[22:23], v[216:217]
	s_waitcnt vmcnt(14)
	v_pk_add_f32 v[136:137], v[20:21], v[234:235]
	v_pk_add_f32 v[134:135], v[18:19], v[232:233]
	s_waitcnt vmcnt(13)
	v_pk_add_f32 v[140:141], v[8:9], v[238:239]
	v_pk_add_f32 v[138:139], v[6:7], v[236:237]
	s_waitcnt vmcnt(12)
	v_pk_add_f32 v[144:145], v[4:5], v[242:243]
	v_pk_add_f32 v[142:143], v[2:3], v[240:241]
	global_store_dwordx4 v[212:213], v[130:133], off nt
	global_store_dwordx4 v[212:213], v[134:137], off offset:64 nt
	global_store_dwordx4 v[212:213], v[138:141], off offset:512 nt
	global_store_dwordx4 v[212:213], v[142:145], off offset:576 nt
.LBB0_385:
	s_and_b64 vcc, exec, s[48:49]
	s_cbranch_vccz .LBB0_387
	s_lshl_b64 s[48:49], s[88:89], 23
	v_ashrrev_i32_e32 v205, 31, v204
	s_add_u32 s48, s82, s48
	s_addc_u32 s49, s83, s49
	v_lshlrev_b64 v[130:131], 13, v[204:205]
	v_lshl_add_u64 v[130:131], s[48:49], 0, v[130:131]
	v_lshlrev_b64 v[132:133], 2, v[202:203]
	v_lshl_add_u64 v[130:131], v[130:131], 0, v[132:133]
	v_ashrrev_i32_e32 v201, 31, v200
	global_store_dwordx4 v[130:131], v[126:129], off nt
	global_store_dwordx4 v[130:131], v[122:125], off offset:64 nt
	global_store_dwordx4 v[130:131], v[110:113], off offset:512 nt
	global_store_dwordx4 v[130:131], v[106:109], off offset:576 nt
	v_lshlrev_b64 v[130:131], 13, v[200:201]
	v_lshl_add_u64 v[130:131], s[48:49], 0, v[130:131]
	v_lshl_add_u64 v[130:131], v[130:131], 0, v[132:133]
	v_ashrrev_i32_e32 v199, 31, v198
	global_store_dwordx4 v[130:131], v[118:121], off nt
	global_store_dwordx4 v[130:131], v[114:117], off offset:64 nt
	global_store_dwordx4 v[130:131], v[94:97], off offset:512 nt
	global_store_dwordx4 v[130:131], v[90:93], off offset:576 nt
	v_lshlrev_b64 v[130:131], 13, v[198:199]
	v_lshl_add_u64 v[130:131], s[48:49], 0, v[130:131]
	v_lshl_add_u64 v[130:131], v[130:131], 0, v[132:133]
	global_store_dwordx4 v[130:131], v[102:105], off nt
	global_store_dwordx4 v[130:131], v[98:101], off offset:64 nt
	global_store_dwordx4 v[130:131], v[78:81], off offset:512 nt
	global_store_dwordx4 v[130:131], v[74:77], off offset:576 nt
	v_add_u32_e32 v130, 0xffffe030, v196
	v_ashrrev_i32_e32 v131, 31, v130
	v_lshlrev_b64 v[130:131], 13, v[130:131]
	v_lshl_add_u64 v[130:131], s[48:49], 0, v[130:131]
	v_lshl_add_u64 v[130:131], v[130:131], 0, v[132:133]
	global_store_dwordx4 v[130:131], v[86:89], off nt
	global_store_dwordx4 v[130:131], v[82:85], off offset:64 nt
	global_store_dwordx4 v[130:131], v[70:73], off offset:512 nt
	global_store_dwordx4 v[130:131], v[66:69], off offset:576 nt
	v_add_u32_e32 v130, 0xffffe080, v196
	v_ashrrev_i32_e32 v131, 31, v130
	v_lshlrev_b64 v[130:131], 13, v[130:131]
	v_lshl_add_u64 v[130:131], s[48:49], 0, v[130:131]
	v_lshl_add_u64 v[130:131], v[130:131], 0, v[132:133]
	global_store_dwordx4 v[130:131], v[62:65], off nt
	global_store_dwordx4 v[130:131], v[58:61], off offset:64 nt
	global_store_dwordx4 v[130:131], v[46:49], off offset:512 nt
	global_store_dwordx4 v[130:131], v[42:45], off offset:576 nt
	v_add_u32_e32 v130, 0xffffe090, v196
	v_ashrrev_i32_e32 v131, 31, v130
	v_lshlrev_b64 v[130:131], 13, v[130:131]
	v_lshl_add_u64 v[130:131], s[48:49], 0, v[130:131]
	v_lshl_add_u64 v[130:131], v[130:131], 0, v[132:133]
	global_store_dwordx4 v[130:131], v[54:57], off nt
	global_store_dwordx4 v[130:131], v[50:53], off offset:64 nt
	global_store_dwordx4 v[130:131], v[30:33], off offset:512 nt
	global_store_dwordx4 v[130:131], v[26:29], off offset:576 nt
	v_add_u32_e32 v130, 0xffffe0a0, v196
	v_ashrrev_i32_e32 v131, 31, v130
	v_lshlrev_b64 v[130:131], 13, v[130:131]
	v_lshl_add_u64 v[130:131], s[48:49], 0, v[130:131]
	v_lshl_add_u64 v[130:131], v[130:131], 0, v[132:133]
	global_store_dwordx4 v[130:131], v[38:41], off nt
	global_store_dwordx4 v[130:131], v[34:37], off offset:64 nt
	global_store_dwordx4 v[130:131], v[14:17], off offset:512 nt
	global_store_dwordx4 v[130:131], v[10:13], off offset:576 nt
	v_add_u32_e32 v130, 0xffffe0b0, v196
	v_ashrrev_i32_e32 v131, 31, v130
	v_lshlrev_b64 v[130:131], 13, v[130:131]
	v_lshl_add_u64 v[130:131], s[48:49], 0, v[130:131]
	v_lshl_add_u64 v[130:131], v[130:131], 0, v[132:133]
	global_store_dwordx4 v[130:131], v[22:25], off nt
	global_store_dwordx4 v[130:131], v[18:21], off offset:64 nt
	global_store_dwordx4 v[130:131], v[6:9], off offset:512 nt
	global_store_dwordx4 v[130:131], v[2:5], off offset:576 nt

.LBB0_395:
	s_add_u32 s50, s16, s15
	s_addc_u32 s51, s17, 0
	v_cvt_pk_bf16_f32 v138, v138, v139
	v_cvt_pk_bf16_f32 v139, v140, v141
	v_cvt_pk_bf16_f32 v140, v142, v143
	v_cvt_pk_bf16_f32 v141, v144, v145
	v_lshl_add_u64 v[142:143], v[146:147], 1, s[50:51]
	s_mov_b64 s[50:51], 0
	global_store_dwordx4 v[142:143], v[138:141], off nt
.LBB0_396:
	s_and_b64 vcc, exec, s[50:51]
	s_waitcnt vmcnt(0)
	v_sub_f32_e32 v171, 1.0, v134
	v_sub_f32_e32 v170, 1.0, v130
	v_sub_f32_e32 v169, 1.0, v135
	v_sub_f32_e32 v168, 1.0, v131
	v_sub_f32_e32 v167, 1.0, v136
	v_sub_f32_e32 v166, 1.0, v132
	v_sub_f32_e32 v165, 1.0, v137
	v_sub_f32_e32 v164, 1.0, v133
	s_cbranch_vccz .LBB0_398
	v_mul_f32_e32 v139, 0xbfb8aa3b, v122
	v_mul_f32_e32 v140, 0xbfb8aa3b, v127
	v_exp_f32_e32 v139, v139
	v_exp_f32_e32 v140, v140
	v_mul_f32_e32 v141, 0xbfb8aa3b, v128
	v_exp_f32_e32 v141, v141
	v_add_f32_e32 v139, 1.0, v139
	v_rcp_f32_e32 v139, v139
	v_add_f32_e32 v140, 1.0, v140
	v_rcp_f32_e32 v140, v140
	v_add_f32_e32 v141, 1.0, v141
	v_fma_f32 v139, v139, v170, v130
	v_log_f32_e32 v142, v139
	v_fma_f32 v139, v140, v169, v135
	v_mul_f32_e32 v140, 0xbfb8aa3b, v123
	v_exp_f32_e32 v140, v140
	v_mul_f32_e32 v143, 0xbfb8aa3b, v124
	v_rcp_f32_e32 v141, v141
	v_exp_f32_e32 v143, v143
	v_add_f32_e32 v140, 1.0, v140
	v_rcp_f32_e32 v140, v140
	v_mul_f32_e32 v138, 0xbfb8aa3b, v126
	v_exp_f32_e32 v138, v138
	v_mul_f32_e32 v144, 0xbfb8aa3b, v125
	v_fma_f32 v150, v140, v168, v131
	v_fma_f32 v140, v141, v167, v136
	v_add_f32_e32 v141, 1.0, v143
	v_mul_f32_e32 v143, 0xbfb8aa3b, v129
	v_exp_f32_e32 v143, v143
	v_exp_f32_e32 v144, v144
	v_add_f32_e32 v138, 1.0, v138
	v_rcp_f32_e32 v141, v141
	v_add_f32_e32 v143, 1.0, v143
	v_rcp_f32_e32 v138, v138
	v_rcp_f32_e32 v143, v143
	v_add_f32_e32 v144, 1.0, v144
	v_rcp_f32_e32 v145, v144
	v_fma_f32 v141, v141, v166, v132
	v_fma_f32 v138, v138, v171, v134
	v_log_f32_e32 v144, v141
	v_fma_f32 v141, v143, v165, v137
	v_log_f32_e32 v138, v138
	v_log_f32_e32 v139, v139
	v_log_f32_e32 v140, v140
	v_log_f32_e32 v141, v141
	v_fma_f32 v143, v145, v164, v133
	v_log_f32_e32 v145, v143
	v_log_f32_e32 v143, v150
	v_pk_mul_f32 v[140:141], v[140:141], s[96:97] op_sel_hi:[1,0]
	v_pk_mul_f32 v[138:139], v[138:139], s[96:97] op_sel_hi:[1,0]
	v_lshl_add_u64 v[146:147], v[146:147], 2, s[28:29]
	v_pk_mul_f32 v[144:145], v[144:145], s[96:97] op_sel_hi:[1,0]
	v_pk_mul_f32 v[142:143], v[142:143], s[96:97] op_sel_hi:[1,0]
	global_store_dwordx4 v[146:147], v[138:141], off nt
	global_store_dwordx4 v[146:147], v[142:145], off offset:16 nt

.LBB0_401:
	s_add_u32 s56, s16, s15
	s_addc_u32 s57, s17, 0
	v_cvt_pk_bf16_f32 v138, v138, v139
	v_cvt_pk_bf16_f32 v139, v140, v141
	v_cvt_pk_bf16_f32 v140, v142, v143
	v_cvt_pk_bf16_f32 v141, v144, v145
	v_lshl_add_u64 v[142:143], v[146:147], 1, s[56:57]
	s_mov_b64 s[56:57], 0
	global_store_dwordx4 v[142:143], v[138:141], off nt
.LBB0_402:
	s_and_b64 vcc, exec, s[56:57]
	s_cbranch_vccz .LBB0_404
	v_mul_f32_e32 v139, 0xbfb8aa3b, v114
	v_mul_f32_e32 v140, 0xbfb8aa3b, v119
	v_exp_f32_e32 v139, v139
	v_exp_f32_e32 v140, v140
	v_mul_f32_e32 v141, 0xbfb8aa3b, v120
	v_exp_f32_e32 v141, v141
	v_add_f32_e32 v139, 1.0, v139
	v_rcp_f32_e32 v139, v139
	v_add_f32_e32 v140, 1.0, v140
	v_rcp_f32_e32 v140, v140
	v_add_f32_e32 v141, 1.0, v141
	v_fma_f32 v139, v139, v170, v130
	v_log_f32_e32 v142, v139
	v_fma_f32 v139, v140, v169, v135
	v_mul_f32_e32 v140, 0xbfb8aa3b, v115
	v_exp_f32_e32 v140, v140
	v_mul_f32_e32 v143, 0xbfb8aa3b, v116
	v_rcp_f32_e32 v141, v141
	v_exp_f32_e32 v143, v143
	v_add_f32_e32 v140, 1.0, v140
	v_rcp_f32_e32 v140, v140
	v_mul_f32_e32 v138, 0xbfb8aa3b, v118
	v_exp_f32_e32 v138, v138
	v_mul_f32_e32 v144, 0xbfb8aa3b, v117
	v_fma_f32 v152, v140, v168, v131
	v_fma_f32 v140, v141, v167, v136
	v_add_f32_e32 v141, 1.0, v143
	v_mul_f32_e32 v143, 0xbfb8aa3b, v121
	v_exp_f32_e32 v143, v143
	v_exp_f32_e32 v144, v144
	v_add_f32_e32 v138, 1.0, v138
	v_rcp_f32_e32 v141, v141
	v_add_f32_e32 v143, 1.0, v143
	v_rcp_f32_e32 v138, v138
	v_rcp_f32_e32 v143, v143
	v_add_f32_e32 v144, 1.0, v144
	v_rcp_f32_e32 v145, v144
	v_fma_f32 v141, v141, v166, v132
	v_fma_f32 v138, v138, v171, v134
	v_log_f32_e32 v144, v141
	v_fma_f32 v141, v143, v165, v137
	v_log_f32_e32 v138, v138
	v_log_f32_e32 v139, v139
	v_log_f32_e32 v140, v140
	v_log_f32_e32 v141, v141
	v_fma_f32 v143, v145, v164, v133
	v_log_f32_e32 v145, v143
	v_log_f32_e32 v143, v152
	v_pk_mul_f32 v[140:141], v[140:141], s[96:97] op_sel_hi:[1,0]
	v_pk_mul_f32 v[138:139], v[138:139], s[96:97] op_sel_hi:[1,0]
	v_lshl_add_u64 v[146:147], v[146:147], 2, s[28:29]
	v_pk_mul_f32 v[144:145], v[144:145], s[96:97] op_sel_hi:[1,0]
	v_pk_mul_f32 v[142:143], v[142:143], s[96:97] op_sel_hi:[1,0]
	global_store_dwordx4 v[146:147], v[138:141], off nt
	global_store_dwordx4 v[146:147], v[142:145], off offset:16 nt

.LBB0_408:
	s_and_b64 vcc, exec, s[56:57]
	s_cbranch_vccz .LBB0_410
	v_mul_f32_e32 v139, 0xbfb8aa3b, v98
	v_mul_f32_e32 v140, 0xbfb8aa3b, v103
	v_exp_f32_e32 v139, v139
	v_exp_f32_e32 v140, v140
	v_mul_f32_e32 v141, 0xbfb8aa3b, v104
	v_exp_f32_e32 v141, v141
	v_add_f32_e32 v139, 1.0, v139
	v_rcp_f32_e32 v139, v139
	v_add_f32_e32 v140, 1.0, v140
	v_rcp_f32_e32 v140, v140
	v_add_f32_e32 v141, 1.0, v141
	v_fma_f32 v139, v139, v170, v130
	v_log_f32_e32 v142, v139
	v_fma_f32 v139, v140, v169, v135
	v_mul_f32_e32 v140, 0xbfb8aa3b, v99
	v_exp_f32_e32 v140, v140
	v_mul_f32_e32 v143, 0xbfb8aa3b, v100
	v_rcp_f32_e32 v141, v141
	v_exp_f32_e32 v143, v143
	v_add_f32_e32 v140, 1.0, v140
	v_rcp_f32_e32 v140, v140
	v_mul_f32_e32 v138, 0xbfb8aa3b, v102
	v_exp_f32_e32 v138, v138
	v_mul_f32_e32 v144, 0xbfb8aa3b, v101
	v_fma_f32 v154, v140, v168, v131
	v_fma_f32 v140, v141, v167, v136
	v_add_f32_e32 v141, 1.0, v143
	v_mul_f32_e32 v143, 0xbfb8aa3b, v105
	v_exp_f32_e32 v143, v143
	v_exp_f32_e32 v144, v144
	v_add_f32_e32 v138, 1.0, v138
	v_rcp_f32_e32 v141, v141
	v_add_f32_e32 v143, 1.0, v143
	v_rcp_f32_e32 v138, v138
	v_rcp_f32_e32 v143, v143
	v_add_f32_e32 v144, 1.0, v144
	v_rcp_f32_e32 v145, v144
	v_fma_f32 v141, v141, v166, v132
	v_fma_f32 v138, v138, v171, v134
	v_log_f32_e32 v144, v141
	v_fma_f32 v141, v143, v165, v137
	v_log_f32_e32 v138, v138
	v_log_f32_e32 v139, v139
	v_log_f32_e32 v140, v140
	v_log_f32_e32 v141, v141
	v_fma_f32 v143, v145, v164, v133
	v_log_f32_e32 v145, v143
	v_log_f32_e32 v143, v154
	v_pk_mul_f32 v[140:141], v[140:141], s[96:97] op_sel_hi:[1,0]
	v_pk_mul_f32 v[138:139], v[138:139], s[96:97] op_sel_hi:[1,0]
	v_lshl_add_u64 v[146:147], v[146:147], 2, s[28:29]
	v_pk_mul_f32 v[144:145], v[144:145], s[96:97] op_sel_hi:[1,0]
	v_pk_mul_f32 v[142:143], v[142:143], s[96:97] op_sel_hi:[1,0]
	global_store_dwordx4 v[146:147], v[138:141], off nt
	global_store_dwordx4 v[146:147], v[142:145], off offset:16 nt

.LBB0_414:
	s_and_b64 vcc, exec, s[56:57]
	s_cbranch_vccz .LBB0_416
	v_mul_f32_e32 v139, 0xbfb8aa3b, v82
	v_mul_f32_e32 v140, 0xbfb8aa3b, v87
	v_exp_f32_e32 v139, v139
	v_exp_f32_e32 v140, v140
	v_mul_f32_e32 v141, 0xbfb8aa3b, v88
	v_exp_f32_e32 v141, v141
	v_add_f32_e32 v139, 1.0, v139
	v_rcp_f32_e32 v139, v139
	v_add_f32_e32 v140, 1.0, v140
	v_rcp_f32_e32 v140, v140
	v_add_f32_e32 v141, 1.0, v141
	v_fma_f32 v139, v139, v170, v130
	v_log_f32_e32 v142, v139
	v_fma_f32 v139, v140, v169, v135
	v_mul_f32_e32 v140, 0xbfb8aa3b, v83
	v_exp_f32_e32 v140, v140
	v_mul_f32_e32 v143, 0xbfb8aa3b, v84
	v_rcp_f32_e32 v141, v141
	v_exp_f32_e32 v143, v143
	v_add_f32_e32 v140, 1.0, v140
	v_rcp_f32_e32 v140, v140
	v_mul_f32_e32 v138, 0xbfb8aa3b, v86
	v_exp_f32_e32 v138, v138
	v_mul_f32_e32 v144, 0xbfb8aa3b, v85
	v_fma_f32 v156, v140, v168, v131
	v_fma_f32 v140, v141, v167, v136
	v_add_f32_e32 v141, 1.0, v143
	v_mul_f32_e32 v143, 0xbfb8aa3b, v89
	v_exp_f32_e32 v143, v143
	v_exp_f32_e32 v144, v144
	v_add_f32_e32 v138, 1.0, v138
	v_rcp_f32_e32 v141, v141
	v_add_f32_e32 v143, 1.0, v143
	v_rcp_f32_e32 v138, v138
	v_rcp_f32_e32 v143, v143
	v_add_f32_e32 v144, 1.0, v144
	v_rcp_f32_e32 v145, v144
	v_fma_f32 v141, v141, v166, v132
	v_fma_f32 v138, v138, v171, v134
	v_log_f32_e32 v144, v141
	v_fma_f32 v141, v143, v165, v137
	v_log_f32_e32 v138, v138
	v_log_f32_e32 v139, v139
	v_log_f32_e32 v140, v140
	v_log_f32_e32 v141, v141
	v_fma_f32 v143, v145, v164, v133
	v_log_f32_e32 v145, v143
	v_log_f32_e32 v143, v156
	v_pk_mul_f32 v[140:141], v[140:141], s[96:97] op_sel_hi:[1,0]
	v_pk_mul_f32 v[138:139], v[138:139], s[96:97] op_sel_hi:[1,0]
	v_lshl_add_u64 v[146:147], v[146:147], 2, s[28:29]
	v_pk_mul_f32 v[144:145], v[144:145], s[96:97] op_sel_hi:[1,0]
	v_pk_mul_f32 v[142:143], v[142:143], s[96:97] op_sel_hi:[1,0]
	global_store_dwordx4 v[146:147], v[138:141], off nt
	global_store_dwordx4 v[146:147], v[142:145], off offset:16 nt

.LBB0_420:
	s_and_b64 vcc, exec, s[56:57]
	s_cbranch_vccz .LBB0_422
	v_mul_f32_e32 v139, 0xbfb8aa3b, v58
	v_mul_f32_e32 v140, 0xbfb8aa3b, v63
	v_exp_f32_e32 v139, v139
	v_exp_f32_e32 v140, v140
	v_mul_f32_e32 v141, 0xbfb8aa3b, v64
	v_exp_f32_e32 v141, v141
	v_add_f32_e32 v139, 1.0, v139
	v_rcp_f32_e32 v139, v139
	v_add_f32_e32 v140, 1.0, v140
	v_rcp_f32_e32 v140, v140
	v_add_f32_e32 v141, 1.0, v141
	v_fma_f32 v139, v139, v170, v130
	v_log_f32_e32 v142, v139
	v_fma_f32 v139, v140, v169, v135
	v_mul_f32_e32 v140, 0xbfb8aa3b, v59
	v_exp_f32_e32 v140, v140
	v_mul_f32_e32 v143, 0xbfb8aa3b, v60
	v_rcp_f32_e32 v141, v141
	v_exp_f32_e32 v143, v143
	v_add_f32_e32 v140, 1.0, v140
	v_rcp_f32_e32 v140, v140
	v_mul_f32_e32 v138, 0xbfb8aa3b, v62
	v_exp_f32_e32 v138, v138
	v_mul_f32_e32 v144, 0xbfb8aa3b, v61
	v_fma_f32 v158, v140, v168, v131
	v_fma_f32 v140, v141, v167, v136
	v_add_f32_e32 v141, 1.0, v143
	v_mul_f32_e32 v143, 0xbfb8aa3b, v65
	v_exp_f32_e32 v143, v143
	v_exp_f32_e32 v144, v144
	v_add_f32_e32 v138, 1.0, v138
	v_rcp_f32_e32 v141, v141
	v_add_f32_e32 v143, 1.0, v143
	v_rcp_f32_e32 v138, v138
	v_rcp_f32_e32 v143, v143
	v_add_f32_e32 v144, 1.0, v144
	v_rcp_f32_e32 v145, v144
	v_fma_f32 v141, v141, v166, v132
	v_fma_f32 v138, v138, v171, v134
	v_log_f32_e32 v144, v141
	v_fma_f32 v141, v143, v165, v137
	v_log_f32_e32 v138, v138
	v_log_f32_e32 v139, v139
	v_log_f32_e32 v140, v140
	v_log_f32_e32 v141, v141
	v_fma_f32 v143, v145, v164, v133
	v_log_f32_e32 v145, v143
	v_log_f32_e32 v143, v158
	v_pk_mul_f32 v[140:141], v[140:141], s[96:97] op_sel_hi:[1,0]
	v_pk_mul_f32 v[138:139], v[138:139], s[96:97] op_sel_hi:[1,0]
	v_lshl_add_u64 v[146:147], v[146:147], 2, s[28:29]
	v_pk_mul_f32 v[144:145], v[144:145], s[96:97] op_sel_hi:[1,0]
	v_pk_mul_f32 v[142:143], v[142:143], s[96:97] op_sel_hi:[1,0]
	global_store_dwordx4 v[146:147], v[138:141], off nt
	global_store_dwordx4 v[146:147], v[142:145], off offset:16 nt

.LBB0_426:
	s_and_b64 vcc, exec, s[56:57]
	s_cbranch_vccz .LBB0_428
	v_mul_f32_e32 v139, 0xbfb8aa3b, v50
	v_mul_f32_e32 v140, 0xbfb8aa3b, v55
	v_exp_f32_e32 v139, v139
	v_exp_f32_e32 v140, v140
	v_mul_f32_e32 v141, 0xbfb8aa3b, v56
	v_exp_f32_e32 v141, v141
	v_add_f32_e32 v139, 1.0, v139
	v_rcp_f32_e32 v139, v139
	v_add_f32_e32 v140, 1.0, v140
	v_rcp_f32_e32 v140, v140
	v_add_f32_e32 v141, 1.0, v141
	v_fma_f32 v139, v139, v170, v130
	v_log_f32_e32 v142, v139
	v_fma_f32 v139, v140, v169, v135
	v_mul_f32_e32 v140, 0xbfb8aa3b, v51
	v_exp_f32_e32 v140, v140
	v_mul_f32_e32 v143, 0xbfb8aa3b, v52
	v_rcp_f32_e32 v141, v141
	v_exp_f32_e32 v143, v143
	v_add_f32_e32 v140, 1.0, v140
	v_rcp_f32_e32 v140, v140
	v_mul_f32_e32 v138, 0xbfb8aa3b, v54
	v_exp_f32_e32 v138, v138
	v_mul_f32_e32 v144, 0xbfb8aa3b, v53
	v_fma_f32 v160, v140, v168, v131
	v_fma_f32 v140, v141, v167, v136
	v_add_f32_e32 v141, 1.0, v143
	v_mul_f32_e32 v143, 0xbfb8aa3b, v57
	v_exp_f32_e32 v143, v143
	v_exp_f32_e32 v144, v144
	v_add_f32_e32 v138, 1.0, v138
	v_rcp_f32_e32 v141, v141
	v_add_f32_e32 v143, 1.0, v143
	v_rcp_f32_e32 v138, v138
	v_rcp_f32_e32 v143, v143
	v_add_f32_e32 v144, 1.0, v144
	v_rcp_f32_e32 v145, v144
	v_fma_f32 v141, v141, v166, v132
	v_fma_f32 v138, v138, v171, v134
	v_log_f32_e32 v144, v141
	v_fma_f32 v141, v143, v165, v137
	v_log_f32_e32 v138, v138
	v_log_f32_e32 v139, v139
	v_log_f32_e32 v140, v140
	v_log_f32_e32 v141, v141
	v_fma_f32 v143, v145, v164, v133
	v_log_f32_e32 v145, v143
	v_log_f32_e32 v143, v160
	v_pk_mul_f32 v[140:141], v[140:141], s[96:97] op_sel_hi:[1,0]
	v_pk_mul_f32 v[138:139], v[138:139], s[96:97] op_sel_hi:[1,0]
	v_lshl_add_u64 v[146:147], v[146:147], 2, s[28:29]
	v_pk_mul_f32 v[144:145], v[144:145], s[96:97] op_sel_hi:[1,0]
	v_pk_mul_f32 v[142:143], v[142:143], s[96:97] op_sel_hi:[1,0]
	global_store_dwordx4 v[146:147], v[138:141], off nt
	global_store_dwordx4 v[146:147], v[142:145], off offset:16 nt

.LBB0_432:
	s_and_b64 vcc, exec, s[56:57]
	s_cbranch_vccz .LBB0_434
	v_mul_f32_e32 v139, 0xbfb8aa3b, v34
	v_mul_f32_e32 v140, 0xbfb8aa3b, v39
	v_exp_f32_e32 v139, v139
	v_exp_f32_e32 v140, v140
	v_mul_f32_e32 v141, 0xbfb8aa3b, v40
	v_exp_f32_e32 v141, v141
	v_add_f32_e32 v139, 1.0, v139
	v_rcp_f32_e32 v139, v139
	v_add_f32_e32 v140, 1.0, v140
	v_rcp_f32_e32 v140, v140
	v_add_f32_e32 v141, 1.0, v141
	v_fma_f32 v139, v139, v170, v130
	v_log_f32_e32 v142, v139
	v_fma_f32 v139, v140, v169, v135
	v_mul_f32_e32 v140, 0xbfb8aa3b, v35
	v_exp_f32_e32 v140, v140
	v_mul_f32_e32 v143, 0xbfb8aa3b, v36
	v_rcp_f32_e32 v141, v141
	v_exp_f32_e32 v143, v143
	v_add_f32_e32 v140, 1.0, v140
	v_rcp_f32_e32 v140, v140
	v_mul_f32_e32 v138, 0xbfb8aa3b, v38
	v_exp_f32_e32 v138, v138
	v_mul_f32_e32 v144, 0xbfb8aa3b, v37
	v_fma_f32 v162, v140, v168, v131
	v_fma_f32 v140, v141, v167, v136
	v_add_f32_e32 v141, 1.0, v143
	v_mul_f32_e32 v143, 0xbfb8aa3b, v41
	v_exp_f32_e32 v143, v143
	v_exp_f32_e32 v144, v144
	v_add_f32_e32 v138, 1.0, v138
	v_rcp_f32_e32 v141, v141
	v_add_f32_e32 v143, 1.0, v143
	v_rcp_f32_e32 v138, v138
	v_rcp_f32_e32 v143, v143
	v_add_f32_e32 v144, 1.0, v144
	v_rcp_f32_e32 v145, v144
	v_fma_f32 v141, v141, v166, v132
	v_fma_f32 v138, v138, v171, v134
	v_log_f32_e32 v144, v141
	v_fma_f32 v141, v143, v165, v137
	v_log_f32_e32 v138, v138
	v_log_f32_e32 v139, v139
	v_log_f32_e32 v140, v140
	v_log_f32_e32 v141, v141
	v_fma_f32 v143, v145, v164, v133
	v_log_f32_e32 v145, v143
	v_log_f32_e32 v143, v162
	v_pk_mul_f32 v[140:141], v[140:141], s[96:97] op_sel_hi:[1,0]
	v_pk_mul_f32 v[138:139], v[138:139], s[96:97] op_sel_hi:[1,0]
	v_lshl_add_u64 v[146:147], v[146:147], 2, s[28:29]
	v_pk_mul_f32 v[144:145], v[144:145], s[96:97] op_sel_hi:[1,0]
	v_pk_mul_f32 v[142:143], v[142:143], s[96:97] op_sel_hi:[1,0]
	global_store_dwordx4 v[146:147], v[138:141], off nt
	global_store_dwordx4 v[146:147], v[142:145], off offset:16 nt

.LBB0_437:
	s_add_u32 s56, s16, s15
	s_addc_u32 s57, s17, 0
	v_cvt_pk_bf16_f32 v138, v138, v139
	v_cvt_pk_bf16_f32 v139, v140, v141
	v_cvt_pk_bf16_f32 v140, v142, v143
	v_cvt_pk_bf16_f32 v141, v144, v145
	v_lshl_add_u64 v[142:143], v[162:163], 1, s[56:57]
	s_mov_b64 s[56:57], 0
	global_store_dwordx4 v[142:143], v[138:141], off nt
.LBB0_438:
	s_and_b64 vcc, exec, s[56:57]
	s_cbranch_vccz .LBB0_440
	v_mul_f32_e32 v138, 0xbfb8aa3b, v22
	v_exp_f32_e32 v138, v138
	s_nop 0
	v_add_f32_e32 v138, 1.0, v138
	v_rcp_f32_e32 v138, v138
	s_nop 0
	v_fmac_f32_e32 v134, v138, v171
	v_mul_f32_e32 v138, 0xbfb8aa3b, v18
	v_exp_f32_e32 v138, v138
	v_log_f32_e32 v134, v134
	v_add_f32_e32 v138, 1.0, v138
	v_rcp_f32_e32 v138, v138
	s_nop 0
	v_fmac_f32_e32 v130, v138, v170
	v_mul_f32_e32 v138, 0xbfb8aa3b, v23
	v_exp_f32_e32 v138, v138
	v_log_f32_e32 v130, v130
	v_add_f32_e32 v138, 1.0, v138
	v_rcp_f32_e32 v138, v138
	s_nop 0
	v_fmac_f32_e32 v135, v138, v169
	v_mul_f32_e32 v138, 0xbfb8aa3b, v19
	v_exp_f32_e32 v138, v138
	v_log_f32_e32 v135, v135
	v_add_f32_e32 v138, 1.0, v138
	v_rcp_f32_e32 v138, v138
	v_pk_mul_f32 v[134:135], v[134:135], s[96:97] op_sel_hi:[1,0]
	v_fmac_f32_e32 v131, v138, v168
	v_mul_f32_e32 v138, 0xbfb8aa3b, v24
	v_exp_f32_e32 v138, v138
	v_log_f32_e32 v131, v131
	v_add_f32_e32 v138, 1.0, v138
	v_rcp_f32_e32 v138, v138
	v_pk_mul_f32 v[130:131], v[130:131], s[96:97] op_sel_hi:[1,0]
	v_fmac_f32_e32 v136, v138, v167
	v_mul_f32_e32 v138, 0xbfb8aa3b, v20
	v_exp_f32_e32 v138, v138
	v_log_f32_e32 v136, v136
	v_add_f32_e32 v138, 1.0, v138
	v_rcp_f32_e32 v138, v138
	s_nop 0
	v_fmac_f32_e32 v132, v138, v166
	v_mul_f32_e32 v138, 0xbfb8aa3b, v25
	v_exp_f32_e32 v138, v138
	v_log_f32_e32 v132, v132
	v_add_f32_e32 v138, 1.0, v138
	v_rcp_f32_e32 v138, v138
	s_nop 0
	v_fmac_f32_e32 v137, v138, v165
	v_mul_f32_e32 v138, 0xbfb8aa3b, v21
	v_exp_f32_e32 v138, v138
	v_log_f32_e32 v137, v137
	v_add_f32_e32 v138, 1.0, v138
	v_rcp_f32_e32 v138, v138
	v_pk_mul_f32 v[136:137], v[136:137], s[96:97] op_sel_hi:[1,0]
	v_fmac_f32_e32 v133, v138, v164
	v_log_f32_e32 v133, v133
	v_lshl_add_u64 v[138:139], v[162:163], 2, s[28:29]
	v_pk_mul_f32 v[132:133], v[132:133], s[96:97] op_sel_hi:[1,0]
	global_store_dwordx4 v[138:139], v[134:137], off nt
	global_store_dwordx4 v[138:139], v[130:133], off offset:16 nt

.LBB0_445:
	s_add_u32 s54, s16, s15
	v_cvt_pk_bf16_f32 v138, v138, v139
	v_cvt_pk_bf16_f32 v139, v140, v141
	v_cvt_pk_bf16_f32 v140, v142, v143
	s_addc_u32 s55, s17, 0
	v_lshl_add_u64 v[142:143], v[148:149], 0, v[0:1]
	v_cvt_pk_bf16_f32 v141, v144, v145
	v_lshl_add_u64 v[142:143], v[142:143], 1, s[54:55]
	s_mov_b64 s[54:55], 0
	global_store_dwordx4 v[142:143], v[138:141], off offset:256 nt
.LBB0_446:
	s_and_b64 vcc, exec, s[54:55]
	s_waitcnt vmcnt(1)
	v_sub_f32_e32 v170, 1.0, v134
	s_waitcnt vmcnt(0)
	v_sub_f32_e32 v169, 1.0, v130
	v_sub_f32_e32 v168, 1.0, v135
	v_sub_f32_e32 v167, 1.0, v131
	v_sub_f32_e32 v166, 1.0, v136
	v_sub_f32_e32 v164, 1.0, v132
	v_sub_f32_e32 v163, 1.0, v137
	v_sub_f32_e32 v162, 1.0, v133
	s_cbranch_vccz .LBB0_468
	v_mul_f32_e32 v139, 0xbfb8aa3b, v106
	v_exp_f32_e32 v139, v139
	v_mul_f32_e32 v140, 0xbfb8aa3b, v111
	v_exp_f32_e32 v140, v140
	v_mul_f32_e32 v141, 0xbfb8aa3b, v112
	v_add_f32_e32 v139, 1.0, v139
	v_rcp_f32_e32 v139, v139
	v_add_f32_e32 v140, 1.0, v140
	v_rcp_f32_e32 v140, v140
	v_exp_f32_e32 v141, v141
	v_fma_f32 v139, v139, v169, v130
	v_log_f32_e32 v142, v139
	v_fma_f32 v139, v140, v168, v135
	v_mul_f32_e32 v140, 0xbfb8aa3b, v107
	v_exp_f32_e32 v140, v140
	v_add_f32_e32 v141, 1.0, v141
	v_mul_f32_e32 v143, 0xbfb8aa3b, v108
	v_rcp_f32_e32 v141, v141
	v_add_f32_e32 v140, 1.0, v140
	v_rcp_f32_e32 v140, v140
	v_exp_f32_e32 v143, v143
	v_mul_f32_e32 v138, 0xbfb8aa3b, v110
	v_exp_f32_e32 v138, v138
	v_fma_f32 v171, v140, v167, v131
	v_fma_f32 v140, v141, v166, v136
	v_add_f32_e32 v141, 1.0, v143
	v_mul_f32_e32 v143, 0xbfb8aa3b, v113
	v_exp_f32_e32 v143, v143
	v_mul_f32_e32 v144, 0xbfb8aa3b, v109
	v_exp_f32_e32 v144, v144
	v_add_f32_e32 v138, 1.0, v138
	v_rcp_f32_e32 v141, v141
	v_add_f32_e32 v143, 1.0, v143
	v_rcp_f32_e32 v138, v138
	v_rcp_f32_e32 v143, v143
	v_add_f32_e32 v144, 1.0, v144
	v_rcp_f32_e32 v145, v144
	v_fma_f32 v141, v141, v164, v132
	v_fma_f32 v138, v138, v170, v134
	v_log_f32_e32 v144, v141
	v_fma_f32 v141, v143, v163, v137
	v_log_f32_e32 v138, v138
	v_log_f32_e32 v139, v139
	v_log_f32_e32 v140, v140
	v_log_f32_e32 v141, v141
	v_fma_f32 v143, v145, v162, v133
	v_log_f32_e32 v145, v143
	v_log_f32_e32 v143, v171
	v_or_b32_e32 v148, v148, v165
	v_pk_mul_f32 v[140:141], v[140:141], s[96:97] op_sel_hi:[1,0]
	v_pk_mul_f32 v[138:139], v[138:139], s[96:97] op_sel_hi:[1,0]
	v_lshl_add_u64 v[148:149], v[148:149], 2, s[28:29]
	v_pk_mul_f32 v[144:145], v[144:145], s[96:97] op_sel_hi:[1,0]
	v_pk_mul_f32 v[142:143], v[142:143], s[96:97] op_sel_hi:[1,0]
	global_store_dwordx4 v[148:149], v[138:141], off nt
	global_store_dwordx4 v[148:149], v[142:145], off offset:16 nt
	s_and_b64 vcc, exec, s[50:51]
	s_mov_b64 s[54:55], -1
	s_cbranch_vccz .LBB0_469
.LBB0_448:
	s_and_b64 vcc, exec, s[54:55]
	s_cbranch_vccz .LBB0_472
	v_mul_f32_e32 v139, 0xbfb8aa3b, v90
	v_exp_f32_e32 v139, v139
	v_mul_f32_e32 v140, 0xbfb8aa3b, v95
	v_exp_f32_e32 v140, v140
	v_mul_f32_e32 v141, 0xbfb8aa3b, v96
	v_add_f32_e32 v139, 1.0, v139
	v_rcp_f32_e32 v139, v139
	v_add_f32_e32 v140, 1.0, v140
	v_rcp_f32_e32 v140, v140
	v_exp_f32_e32 v141, v141
	v_fma_f32 v139, v139, v169, v130
	v_log_f32_e32 v142, v139
	v_fma_f32 v139, v140, v168, v135
	v_mul_f32_e32 v140, 0xbfb8aa3b, v91
	v_exp_f32_e32 v140, v140
	v_add_f32_e32 v141, 1.0, v141
	v_mul_f32_e32 v143, 0xbfb8aa3b, v92
	v_rcp_f32_e32 v141, v141
	v_add_f32_e32 v140, 1.0, v140
	v_rcp_f32_e32 v140, v140
	v_exp_f32_e32 v143, v143
	v_mul_f32_e32 v138, 0xbfb8aa3b, v94
	v_exp_f32_e32 v138, v138
	v_fma_f32 v148, v140, v167, v131
	v_fma_f32 v140, v141, v166, v136
	v_add_f32_e32 v141, 1.0, v143
	v_mul_f32_e32 v143, 0xbfb8aa3b, v97
	v_exp_f32_e32 v143, v143
	v_mul_f32_e32 v144, 0xbfb8aa3b, v93
	v_exp_f32_e32 v144, v144
	v_add_f32_e32 v138, 1.0, v138
	v_rcp_f32_e32 v141, v141
	v_add_f32_e32 v143, 1.0, v143
	v_rcp_f32_e32 v138, v138
	v_rcp_f32_e32 v143, v143
	v_add_f32_e32 v144, 1.0, v144
	v_rcp_f32_e32 v145, v144
	v_fma_f32 v141, v141, v164, v132
	v_fma_f32 v138, v138, v170, v134
	v_log_f32_e32 v144, v141
	v_fma_f32 v141, v143, v163, v137
	v_log_f32_e32 v138, v138
	v_log_f32_e32 v139, v139
	v_log_f32_e32 v140, v140
	v_log_f32_e32 v141, v141
	v_fma_f32 v143, v145, v162, v133
	v_log_f32_e32 v145, v143
	v_log_f32_e32 v143, v148
	v_or_b32_e32 v150, v150, v165
	v_pk_mul_f32 v[140:141], v[140:141], s[96:97] op_sel_hi:[1,0]
	v_pk_mul_f32 v[138:139], v[138:139], s[96:97] op_sel_hi:[1,0]
	v_lshl_add_u64 v[148:149], v[150:151], 2, s[28:29]
	v_pk_mul_f32 v[144:145], v[144:145], s[96:97] op_sel_hi:[1,0]
	v_pk_mul_f32 v[142:143], v[142:143], s[96:97] op_sel_hi:[1,0]
	global_store_dwordx4 v[148:149], v[138:141], off nt
	global_store_dwordx4 v[148:149], v[142:145], off offset:16 nt
	s_and_b64 vcc, exec, s[50:51]
	s_mov_b64 s[54:55], -1
	s_cbranch_vccz .LBB0_473
.LBB0_450:
	s_and_b64 vcc, exec, s[54:55]
	s_cbranch_vccz .LBB0_476
	v_mul_f32_e32 v139, 0xbfb8aa3b, v74
	v_exp_f32_e32 v139, v139
	v_mul_f32_e32 v140, 0xbfb8aa3b, v79
	v_exp_f32_e32 v140, v140
	v_mul_f32_e32 v141, 0xbfb8aa3b, v80
	v_add_f32_e32 v139, 1.0, v139
	v_rcp_f32_e32 v139, v139
	v_add_f32_e32 v140, 1.0, v140
	v_rcp_f32_e32 v140, v140
	v_exp_f32_e32 v141, v141
	v_fma_f32 v139, v139, v169, v130
	v_log_f32_e32 v142, v139
	v_fma_f32 v139, v140, v168, v135
	v_mul_f32_e32 v140, 0xbfb8aa3b, v75
	v_exp_f32_e32 v140, v140
	v_add_f32_e32 v141, 1.0, v141
	v_mul_f32_e32 v143, 0xbfb8aa3b, v76
	v_rcp_f32_e32 v141, v141
	v_add_f32_e32 v140, 1.0, v140
	v_rcp_f32_e32 v140, v140
	v_exp_f32_e32 v143, v143
	v_mul_f32_e32 v138, 0xbfb8aa3b, v78
	v_exp_f32_e32 v138, v138
	v_fma_f32 v148, v140, v167, v131
	v_fma_f32 v140, v141, v166, v136
	v_add_f32_e32 v141, 1.0, v143
	v_mul_f32_e32 v143, 0xbfb8aa3b, v81
	v_exp_f32_e32 v143, v143
	v_mul_f32_e32 v144, 0xbfb8aa3b, v77
	v_exp_f32_e32 v144, v144
	v_add_f32_e32 v138, 1.0, v138
	v_rcp_f32_e32 v141, v141
	v_add_f32_e32 v143, 1.0, v143
	v_rcp_f32_e32 v138, v138
	v_rcp_f32_e32 v143, v143
	v_add_f32_e32 v144, 1.0, v144
	v_rcp_f32_e32 v145, v144
	v_fma_f32 v141, v141, v164, v132
	v_fma_f32 v138, v138, v170, v134
	v_log_f32_e32 v144, v141
	v_fma_f32 v141, v143, v163, v137
	v_log_f32_e32 v138, v138
	v_log_f32_e32 v139, v139
	v_log_f32_e32 v140, v140
	v_log_f32_e32 v141, v141
	v_fma_f32 v143, v145, v162, v133
	v_log_f32_e32 v145, v143
	v_log_f32_e32 v143, v148
	v_or_b32_e32 v152, v152, v165
	v_pk_mul_f32 v[140:141], v[140:141], s[96:97] op_sel_hi:[1,0]
	v_pk_mul_f32 v[138:139], v[138:139], s[96:97] op_sel_hi:[1,0]
	v_lshl_add_u64 v[148:149], v[152:153], 2, s[28:29]
	v_pk_mul_f32 v[144:145], v[144:145], s[96:97] op_sel_hi:[1,0]
	v_pk_mul_f32 v[142:143], v[142:143], s[96:97] op_sel_hi:[1,0]
	global_store_dwordx4 v[148:149], v[138:141], off nt
	global_store_dwordx4 v[148:149], v[142:145], off offset:16 nt
	s_and_b64 vcc, exec, s[50:51]
	s_mov_b64 s[54:55], -1
	s_cbranch_vccz .LBB0_477
.LBB0_452:
	s_and_b64 vcc, exec, s[54:55]
	s_cbranch_vccz .LBB0_480
	v_mul_f32_e32 v139, 0xbfb8aa3b, v66
	v_exp_f32_e32 v139, v139
	v_mul_f32_e32 v140, 0xbfb8aa3b, v71
	v_exp_f32_e32 v140, v140
	v_mul_f32_e32 v141, 0xbfb8aa3b, v72
	v_add_f32_e32 v139, 1.0, v139
	v_rcp_f32_e32 v139, v139
	v_add_f32_e32 v140, 1.0, v140
	v_rcp_f32_e32 v140, v140
	v_exp_f32_e32 v141, v141
	v_fma_f32 v139, v139, v169, v130
	v_log_f32_e32 v142, v139
	v_fma_f32 v139, v140, v168, v135
	v_mul_f32_e32 v140, 0xbfb8aa3b, v67
	v_exp_f32_e32 v140, v140
	v_add_f32_e32 v141, 1.0, v141
	v_mul_f32_e32 v143, 0xbfb8aa3b, v68
	v_rcp_f32_e32 v141, v141
	v_add_f32_e32 v140, 1.0, v140
	v_rcp_f32_e32 v140, v140
	v_exp_f32_e32 v143, v143
	v_mul_f32_e32 v138, 0xbfb8aa3b, v70
	v_exp_f32_e32 v138, v138
	v_fma_f32 v148, v140, v167, v131
	v_fma_f32 v140, v141, v166, v136
	v_add_f32_e32 v141, 1.0, v143
	v_mul_f32_e32 v143, 0xbfb8aa3b, v73
	v_exp_f32_e32 v143, v143
	v_mul_f32_e32 v144, 0xbfb8aa3b, v69
	v_exp_f32_e32 v144, v144
	v_add_f32_e32 v138, 1.0, v138
	v_rcp_f32_e32 v141, v141
	v_add_f32_e32 v143, 1.0, v143
	v_rcp_f32_e32 v138, v138
	v_rcp_f32_e32 v143, v143
	v_add_f32_e32 v144, 1.0, v144
	v_rcp_f32_e32 v145, v144
	v_fma_f32 v141, v141, v164, v132
	v_fma_f32 v138, v138, v170, v134
	v_log_f32_e32 v144, v141
	v_fma_f32 v141, v143, v163, v137
	v_log_f32_e32 v138, v138
	v_log_f32_e32 v139, v139
	v_log_f32_e32 v140, v140
	v_log_f32_e32 v141, v141
	v_fma_f32 v143, v145, v162, v133
	v_log_f32_e32 v145, v143
	v_log_f32_e32 v143, v148
	v_or_b32_e32 v154, v154, v165
	v_pk_mul_f32 v[140:141], v[140:141], s[96:97] op_sel_hi:[1,0]
	v_pk_mul_f32 v[138:139], v[138:139], s[96:97] op_sel_hi:[1,0]
	v_lshl_add_u64 v[148:149], v[154:155], 2, s[28:29]
	v_pk_mul_f32 v[144:145], v[144:145], s[96:97] op_sel_hi:[1,0]
	v_pk_mul_f32 v[142:143], v[142:143], s[96:97] op_sel_hi:[1,0]
	global_store_dwordx4 v[148:149], v[138:141], off nt
	global_store_dwordx4 v[148:149], v[142:145], off offset:16 nt
	s_and_b64 vcc, exec, s[50:51]
	s_mov_b64 s[54:55], -1
	s_cbranch_vccz .LBB0_481
.LBB0_454:
	s_and_b64 vcc, exec, s[54:55]
	s_cbranch_vccz .LBB0_484
	v_mul_f32_e32 v139, 0xbfb8aa3b, v42
	v_exp_f32_e32 v139, v139
	v_mul_f32_e32 v140, 0xbfb8aa3b, v47
	v_exp_f32_e32 v140, v140
	v_mul_f32_e32 v141, 0xbfb8aa3b, v48
	v_add_f32_e32 v139, 1.0, v139
	v_rcp_f32_e32 v139, v139
	v_add_f32_e32 v140, 1.0, v140
	v_rcp_f32_e32 v140, v140
	v_exp_f32_e32 v141, v141
	v_fma_f32 v139, v139, v169, v130
	v_log_f32_e32 v142, v139
	v_fma_f32 v139, v140, v168, v135
	v_mul_f32_e32 v140, 0xbfb8aa3b, v43
	v_exp_f32_e32 v140, v140
	v_add_f32_e32 v141, 1.0, v141
	v_mul_f32_e32 v143, 0xbfb8aa3b, v44
	v_rcp_f32_e32 v141, v141
	v_add_f32_e32 v140, 1.0, v140
	v_rcp_f32_e32 v140, v140
	v_exp_f32_e32 v143, v143
	v_mul_f32_e32 v138, 0xbfb8aa3b, v46
	v_exp_f32_e32 v138, v138
	v_fma_f32 v148, v140, v167, v131
	v_fma_f32 v140, v141, v166, v136
	v_add_f32_e32 v141, 1.0, v143
	v_mul_f32_e32 v143, 0xbfb8aa3b, v49
	v_exp_f32_e32 v143, v143
	v_mul_f32_e32 v144, 0xbfb8aa3b, v45
	v_exp_f32_e32 v144, v144
	v_add_f32_e32 v138, 1.0, v138
	v_rcp_f32_e32 v141, v141
	v_add_f32_e32 v143, 1.0, v143
	v_rcp_f32_e32 v138, v138
	v_rcp_f32_e32 v143, v143
	v_add_f32_e32 v144, 1.0, v144
	v_rcp_f32_e32 v145, v144
	v_fma_f32 v141, v141, v164, v132
	v_fma_f32 v138, v138, v170, v134
	v_log_f32_e32 v144, v141
	v_fma_f32 v141, v143, v163, v137
	v_log_f32_e32 v138, v138
	v_log_f32_e32 v139, v139
	v_log_f32_e32 v140, v140
	v_log_f32_e32 v141, v141
	v_fma_f32 v143, v145, v162, v133
	v_log_f32_e32 v145, v143
	v_log_f32_e32 v143, v148
	v_or_b32_e32 v156, v156, v165
	v_pk_mul_f32 v[140:141], v[140:141], s[96:97] op_sel_hi:[1,0]
	v_pk_mul_f32 v[138:139], v[138:139], s[96:97] op_sel_hi:[1,0]
	v_lshl_add_u64 v[148:149], v[156:157], 2, s[28:29]
	v_pk_mul_f32 v[144:145], v[144:145], s[96:97] op_sel_hi:[1,0]
	v_pk_mul_f32 v[142:143], v[142:143], s[96:97] op_sel_hi:[1,0]
	global_store_dwordx4 v[148:149], v[138:141], off nt
	global_store_dwordx4 v[148:149], v[142:145], off offset:16 nt
	s_and_b64 vcc, exec, s[50:51]
	s_mov_b64 s[54:55], -1
	s_cbranch_vccz .LBB0_485
.LBB0_456:
	s_and_b64 vcc, exec, s[54:55]
	s_cbranch_vccz .LBB0_488
	v_mul_f32_e32 v139, 0xbfb8aa3b, v26
	v_exp_f32_e32 v139, v139
	v_mul_f32_e32 v140, 0xbfb8aa3b, v31
	v_exp_f32_e32 v140, v140
	v_mul_f32_e32 v141, 0xbfb8aa3b, v32
	v_add_f32_e32 v139, 1.0, v139
	v_rcp_f32_e32 v139, v139
	v_add_f32_e32 v140, 1.0, v140
	v_rcp_f32_e32 v140, v140
	v_exp_f32_e32 v141, v141
	v_fma_f32 v139, v139, v169, v130
	v_log_f32_e32 v142, v139
	v_fma_f32 v139, v140, v168, v135
	v_mul_f32_e32 v140, 0xbfb8aa3b, v27
	v_exp_f32_e32 v140, v140
	v_add_f32_e32 v141, 1.0, v141
	v_mul_f32_e32 v143, 0xbfb8aa3b, v28
	v_rcp_f32_e32 v141, v141
	v_add_f32_e32 v140, 1.0, v140
	v_rcp_f32_e32 v140, v140
	v_exp_f32_e32 v143, v143
	v_mul_f32_e32 v138, 0xbfb8aa3b, v30
	v_exp_f32_e32 v138, v138
	v_fma_f32 v148, v140, v167, v131
	v_fma_f32 v140, v141, v166, v136
	v_add_f32_e32 v141, 1.0, v143
	v_mul_f32_e32 v143, 0xbfb8aa3b, v33
	v_exp_f32_e32 v143, v143
	v_mul_f32_e32 v144, 0xbfb8aa3b, v29
	v_exp_f32_e32 v144, v144
	v_add_f32_e32 v138, 1.0, v138
	v_rcp_f32_e32 v141, v141
	v_add_f32_e32 v143, 1.0, v143
	v_rcp_f32_e32 v138, v138
	v_rcp_f32_e32 v143, v143
	v_add_f32_e32 v144, 1.0, v144
	v_rcp_f32_e32 v145, v144
	v_fma_f32 v141, v141, v164, v132
	v_fma_f32 v138, v138, v170, v134
	v_log_f32_e32 v144, v141
	v_fma_f32 v141, v143, v163, v137
	v_log_f32_e32 v138, v138
	v_log_f32_e32 v139, v139
	v_log_f32_e32 v140, v140
	v_log_f32_e32 v141, v141
	v_fma_f32 v143, v145, v162, v133
	v_log_f32_e32 v145, v143
	v_log_f32_e32 v143, v148
	v_or_b32_e32 v158, v158, v165
	v_pk_mul_f32 v[140:141], v[140:141], s[96:97] op_sel_hi:[1,0]
	v_pk_mul_f32 v[138:139], v[138:139], s[96:97] op_sel_hi:[1,0]
	v_lshl_add_u64 v[148:149], v[158:159], 2, s[28:29]
	v_pk_mul_f32 v[144:145], v[144:145], s[96:97] op_sel_hi:[1,0]
	v_pk_mul_f32 v[142:143], v[142:143], s[96:97] op_sel_hi:[1,0]
	global_store_dwordx4 v[148:149], v[138:141], off nt
	global_store_dwordx4 v[148:149], v[142:145], off offset:16 nt
	s_and_b64 vcc, exec, s[50:51]
	s_mov_b64 s[54:55], -1
	s_cbranch_vccz .LBB0_489
.LBB0_458:
	s_and_b64 vcc, exec, s[54:55]
	s_cbranch_vccz .LBB0_492
	v_mul_f32_e32 v139, 0xbfb8aa3b, v10
	v_exp_f32_e32 v139, v139
	v_mul_f32_e32 v140, 0xbfb8aa3b, v15
	v_exp_f32_e32 v140, v140
	v_mul_f32_e32 v141, 0xbfb8aa3b, v16
	v_add_f32_e32 v139, 1.0, v139
	v_rcp_f32_e32 v139, v139
	v_add_f32_e32 v140, 1.0, v140
	v_rcp_f32_e32 v140, v140
	v_exp_f32_e32 v141, v141
	v_fma_f32 v139, v139, v169, v130
	v_log_f32_e32 v142, v139
	v_fma_f32 v139, v140, v168, v135
	v_mul_f32_e32 v140, 0xbfb8aa3b, v11
	v_exp_f32_e32 v140, v140
	v_add_f32_e32 v141, 1.0, v141
	v_mul_f32_e32 v143, 0xbfb8aa3b, v12
	v_rcp_f32_e32 v141, v141
	v_add_f32_e32 v140, 1.0, v140
	v_rcp_f32_e32 v140, v140
	v_exp_f32_e32 v143, v143
	v_mul_f32_e32 v138, 0xbfb8aa3b, v14
	v_exp_f32_e32 v138, v138
	v_fma_f32 v148, v140, v167, v131
	v_fma_f32 v140, v141, v166, v136
	v_add_f32_e32 v141, 1.0, v143
	v_mul_f32_e32 v143, 0xbfb8aa3b, v17
	v_exp_f32_e32 v143, v143
	v_mul_f32_e32 v144, 0xbfb8aa3b, v13
	v_exp_f32_e32 v144, v144
	v_add_f32_e32 v138, 1.0, v138
	v_rcp_f32_e32 v141, v141
	v_add_f32_e32 v143, 1.0, v143
	v_rcp_f32_e32 v138, v138
	v_rcp_f32_e32 v143, v143
	v_add_f32_e32 v144, 1.0, v144
	v_rcp_f32_e32 v145, v144
	v_fma_f32 v141, v141, v164, v132
	v_fma_f32 v138, v138, v170, v134
	v_log_f32_e32 v144, v141
	v_fma_f32 v141, v143, v163, v137
	v_log_f32_e32 v138, v138
	v_log_f32_e32 v139, v139
	v_log_f32_e32 v140, v140
	v_log_f32_e32 v141, v141
	v_fma_f32 v143, v145, v162, v133
	v_log_f32_e32 v145, v143
	v_log_f32_e32 v143, v148
	v_or_b32_e32 v160, v160, v165
	v_pk_mul_f32 v[140:141], v[140:141], s[96:97] op_sel_hi:[1,0]
	v_pk_mul_f32 v[138:139], v[138:139], s[96:97] op_sel_hi:[1,0]
	v_lshl_add_u64 v[148:149], v[160:161], 2, s[28:29]
	v_pk_mul_f32 v[144:145], v[144:145], s[96:97] op_sel_hi:[1,0]
	v_pk_mul_f32 v[142:143], v[142:143], s[96:97] op_sel_hi:[1,0]
	global_store_dwordx4 v[148:149], v[138:141], off nt
	global_store_dwordx4 v[148:149], v[142:145], off offset:16 nt
	s_and_b64 vcc, exec, s[50:51]
	s_mov_b64 s[50:51], -1
	s_cbranch_vccz .LBB0_493
.LBB0_460:
	s_and_b64 vcc, exec, s[50:51]
	s_cbranch_vccz .LBB0_462
	v_mul_f32_e32 v0, 0xbfb8aa3b, v6
	v_exp_f32_e32 v0, v0
	v_or_b32_e32 v146, v146, v165
	v_lshl_add_u64 v[138:139], v[146:147], 2, s[28:29]
	v_add_f32_e32 v0, 1.0, v0
	v_rcp_f32_e32 v0, v0
	s_nop 0
	v_fmac_f32_e32 v134, v0, v170
	v_mul_f32_e32 v0, 0xbfb8aa3b, v2
	v_exp_f32_e32 v0, v0
	v_log_f32_e32 v134, v134
	v_add_f32_e32 v0, 1.0, v0
	v_rcp_f32_e32 v0, v0
	s_nop 0
	v_fmac_f32_e32 v130, v0, v169
	v_mul_f32_e32 v0, 0xbfb8aa3b, v7
	v_exp_f32_e32 v0, v0
	v_log_f32_e32 v130, v130
	v_add_f32_e32 v0, 1.0, v0
	v_rcp_f32_e32 v0, v0
	s_nop 0
	v_fmac_f32_e32 v135, v0, v168
	v_mul_f32_e32 v0, 0xbfb8aa3b, v3
	v_exp_f32_e32 v0, v0
	v_log_f32_e32 v135, v135
	v_add_f32_e32 v0, 1.0, v0
	v_rcp_f32_e32 v0, v0
	v_pk_mul_f32 v[134:135], v[134:135], s[96:97] op_sel_hi:[1,0]
	v_fmac_f32_e32 v131, v0, v167
	v_mul_f32_e32 v0, 0xbfb8aa3b, v8
	v_exp_f32_e32 v0, v0
	v_log_f32_e32 v131, v131
	v_add_f32_e32 v0, 1.0, v0
	v_rcp_f32_e32 v0, v0
	v_pk_mul_f32 v[130:131], v[130:131], s[96:97] op_sel_hi:[1,0]
	v_fmac_f32_e32 v136, v0, v166
	v_mul_f32_e32 v0, 0xbfb8aa3b, v4
	v_exp_f32_e32 v0, v0
	v_log_f32_e32 v136, v136
	v_add_f32_e32 v0, 1.0, v0
	v_rcp_f32_e32 v0, v0
	s_nop 0
	v_fmac_f32_e32 v132, v0, v164
	v_mul_f32_e32 v0, 0xbfb8aa3b, v9
	v_exp_f32_e32 v0, v0
	v_log_f32_e32 v132, v132
	v_add_f32_e32 v0, 1.0, v0
	v_rcp_f32_e32 v0, v0
	s_nop 0
	v_fmac_f32_e32 v137, v0, v163
	v_mul_f32_e32 v0, 0xbfb8aa3b, v5
	v_exp_f32_e32 v0, v0
	v_log_f32_e32 v137, v137
	v_add_f32_e32 v0, 1.0, v0
	v_rcp_f32_e32 v0, v0
	v_pk_mul_f32 v[136:137], v[136:137], s[96:97] op_sel_hi:[1,0]
	v_fmac_f32_e32 v133, v0, v162
	v_log_f32_e32 v133, v133
	s_nop 0
	v_pk_mul_f32 v[132:133], v[132:133], s[96:97] op_sel_hi:[1,0]
	global_store_dwordx4 v[138:139], v[134:137], off nt
	global_store_dwordx4 v[138:139], v[130:133], off offset:16 nt

.LBB0_463:
	s_and_b64 vcc, exec, s[48:49]
	s_cbranch_vccz .LBB0_465
	v_lshl_or_b32 v130, s23, 8, v224
	v_or_b32_e32 v0, 16, v196
	v_ashrrev_i32_e32 v131, 31, v130
	v_mad_i64_i32 v[132:133], s[48:49], s4, v196, 0
	v_cvt_pk_bf16_f32 v110, v110, v111
	v_cvt_pk_bf16_f32 v111, v112, v113
	v_cvt_pk_bf16_f32 v112, v106, v107
	v_mad_i64_i32 v[106:107], s[48:49], s4, v0, 0
	v_or_b32_e32 v0, 32, v196
	v_lshl_add_u64 v[132:133], v[132:133], 1, s[30:31]
	v_lshlrev_b64 v[130:131], 1, v[130:131]
	v_cvt_pk_bf16_f32 v94, v94, v95
	v_cvt_pk_bf16_f32 v95, v96, v97
	v_cvt_pk_bf16_f32 v96, v90, v91
	v_mad_i64_i32 v[90:91], s[48:49], s4, v0, 0
	v_or_b32_e32 v0, 48, v196
	v_lshl_add_u64 v[132:133], v[132:133], 0, v[130:131]
	v_cvt_pk_bf16_f32 v113, v108, v109
	v_lshl_add_u64 v[106:107], v[106:107], 1, s[30:31]
	v_cvt_pk_bf16_f32 v78, v78, v79
	v_cvt_pk_bf16_f32 v79, v80, v81
	v_cvt_pk_bf16_f32 v80, v74, v75
	v_mad_i64_i32 v[74:75], s[48:49], s4, v0, 0
	v_add_u32_e32 v0, 0x80, v196
	v_cvt_pk_bf16_f32 v126, v126, v127
	v_cvt_pk_bf16_f32 v127, v128, v129
	v_cvt_pk_bf16_f32 v128, v122, v123
	v_cvt_pk_bf16_f32 v129, v124, v125
	global_store_dwordx4 v[132:133], v[110:113], off offset:256 nt
	v_cvt_pk_bf16_f32 v97, v92, v93
	v_lshl_add_u64 v[90:91], v[90:91], 1, s[30:31]
	v_lshl_add_u64 v[110:111], v[106:107], 0, v[130:131]
	v_cvt_pk_bf16_f32 v70, v70, v71
	v_cvt_pk_bf16_f32 v71, v72, v73
	v_cvt_pk_bf16_f32 v72, v66, v67
	v_mad_i64_i32 v[66:67], s[48:49], s4, v0, 0
	v_add_u32_e32 v0, 0x90, v196
	global_store_dwordx4 v[132:133], v[126:129], off nt
	v_cvt_pk_bf16_f32 v106, v118, v119
	v_cvt_pk_bf16_f32 v107, v120, v121
	v_cvt_pk_bf16_f32 v108, v114, v115
	v_cvt_pk_bf16_f32 v109, v116, v117
	global_store_dwordx4 v[110:111], v[94:97], off offset:256 nt
	v_cvt_pk_bf16_f32 v81, v76, v77
	v_lshl_add_u64 v[74:75], v[74:75], 1, s[30:31]
	v_lshl_add_u64 v[94:95], v[90:91], 0, v[130:131]
	v_lshl_add_u64 v[66:67], v[66:67], 1, s[30:31]
	v_cvt_pk_bf16_f32 v46, v46, v47
	v_cvt_pk_bf16_f32 v47, v48, v49
	v_cvt_pk_bf16_f32 v48, v42, v43
	v_mad_i64_i32 v[42:43], s[48:49], s4, v0, 0
	v_add_u32_e32 v0, 0xa0, v196
	global_store_dwordx4 v[110:111], v[106:109], off nt
	v_cvt_pk_bf16_f32 v90, v102, v103
	v_cvt_pk_bf16_f32 v91, v104, v105
	v_cvt_pk_bf16_f32 v92, v98, v99
	v_cvt_pk_bf16_f32 v93, v100, v101
	global_store_dwordx4 v[94:95], v[78:81], off offset:256 nt
	v_cvt_pk_bf16_f32 v76, v82, v83
	v_cvt_pk_bf16_f32 v77, v84, v85
	v_lshl_add_u64 v[78:79], v[74:75], 0, v[130:131]
	v_cvt_pk_bf16_f32 v74, v86, v87
	v_cvt_pk_bf16_f32 v75, v88, v89
	v_cvt_pk_bf16_f32 v73, v68, v69
	v_lshl_add_u64 v[66:67], v[66:67], 0, v[130:131]
	v_cvt_pk_bf16_f32 v49, v44, v45
	v_lshl_add_u64 v[42:43], v[42:43], 1, s[30:31]
	v_cvt_pk_bf16_f32 v30, v30, v31
	v_cvt_pk_bf16_f32 v31, v32, v33
	v_cvt_pk_bf16_f32 v32, v26, v27
	v_mad_i64_i32 v[26:27], s[48:49], s4, v0, 0
	v_add_u32_e32 v0, 0xb0, v196
	global_store_dwordx4 v[94:95], v[90:93], off nt
	global_store_dwordx4 v[78:79], v[74:77], off nt
	global_store_dwordx4 v[78:79], v[70:73], off offset:256 nt
	v_cvt_pk_bf16_f32 v62, v62, v63
	v_cvt_pk_bf16_f32 v63, v64, v65
	v_cvt_pk_bf16_f32 v64, v58, v59
	v_cvt_pk_bf16_f32 v65, v60, v61
	global_store_dwordx4 v[66:67], v[46:49], off offset:256 nt
	v_cvt_pk_bf16_f32 v33, v28, v29
	v_lshl_add_u64 v[26:27], v[26:27], 1, s[30:31]
	v_lshl_add_u64 v[46:47], v[42:43], 0, v[130:131]
	v_cvt_pk_bf16_f32 v14, v14, v15
	v_cvt_pk_bf16_f32 v15, v16, v17
	v_cvt_pk_bf16_f32 v16, v10, v11
	v_mad_i64_i32 v[10:11], s[48:49], s4, v0, 0
	global_store_dwordx4 v[66:67], v[62:65], off nt
	v_cvt_pk_bf16_f32 v42, v54, v55
	v_cvt_pk_bf16_f32 v43, v56, v57
	v_cvt_pk_bf16_f32 v44, v50, v51
	v_cvt_pk_bf16_f32 v45, v52, v53
	global_store_dwordx4 v[46:47], v[30:33], off offset:256 nt
	v_cvt_pk_bf16_f32 v17, v12, v13
	v_lshl_add_u64 v[10:11], v[10:11], 1, s[30:31]
	v_lshl_add_u64 v[30:31], v[26:27], 0, v[130:131]
	global_store_dwordx4 v[46:47], v[42:45], off nt
	v_cvt_pk_bf16_f32 v26, v38, v39
	v_cvt_pk_bf16_f32 v27, v40, v41
	v_cvt_pk_bf16_f32 v28, v34, v35
	v_cvt_pk_bf16_f32 v29, v36, v37
	global_store_dwordx4 v[30:31], v[14:17], off offset:256 nt
	v_cvt_pk_bf16_f32 v12, v18, v19
	v_cvt_pk_bf16_f32 v13, v20, v21
	v_lshl_add_u64 v[14:15], v[10:11], 0, v[130:131]
	v_cvt_pk_bf16_f32 v10, v22, v23
	v_cvt_pk_bf16_f32 v11, v24, v25
	v_cvt_pk_bf16_f32 v6, v6, v7
	v_cvt_pk_bf16_f32 v7, v8, v9
	v_cvt_pk_bf16_f32 v8, v2, v3
	v_cvt_pk_bf16_f32 v9, v4, v5
	global_store_dwordx4 v[30:31], v[26:29], off nt
	global_store_dwordx4 v[14:15], v[10:13], off nt
	global_store_dwordx4 v[14:15], v[6:9], off offset:256 nt

.LBB0_471:
	s_add_u32 s54, s16, s15
	v_cvt_pk_bf16_f32 v138, v138, v139
	v_cvt_pk_bf16_f32 v139, v140, v141
	v_cvt_pk_bf16_f32 v140, v142, v143
	s_addc_u32 s55, s17, 0
	v_lshl_add_u64 v[142:143], v[150:151], 0, v[0:1]
	v_cvt_pk_bf16_f32 v141, v144, v145
	v_lshl_add_u64 v[142:143], v[142:143], 1, s[54:55]
	global_store_dwordx4 v[142:143], v[138:141], off offset:256 nt

.LBB0_475:
	s_add_u32 s54, s16, s15
	v_cvt_pk_bf16_f32 v138, v138, v139
	v_cvt_pk_bf16_f32 v139, v140, v141
	v_cvt_pk_bf16_f32 v140, v142, v143
	s_addc_u32 s55, s17, 0
	v_lshl_add_u64 v[142:143], v[152:153], 0, v[0:1]
	v_cvt_pk_bf16_f32 v141, v144, v145
	v_lshl_add_u64 v[142:143], v[142:143], 1, s[54:55]
	global_store_dwordx4 v[142:143], v[138:141], off offset:256 nt

.LBB0_479:
	s_add_u32 s54, s16, s15
	v_cvt_pk_bf16_f32 v138, v138, v139
	v_cvt_pk_bf16_f32 v139, v140, v141
	v_cvt_pk_bf16_f32 v140, v142, v143
	s_addc_u32 s55, s17, 0
	v_lshl_add_u64 v[142:143], v[154:155], 0, v[0:1]
	v_cvt_pk_bf16_f32 v141, v144, v145
	v_lshl_add_u64 v[142:143], v[142:143], 1, s[54:55]
	global_store_dwordx4 v[142:143], v[138:141], off offset:256 nt

.LBB0_483:
	s_add_u32 s54, s16, s15
	v_cvt_pk_bf16_f32 v138, v138, v139
	v_cvt_pk_bf16_f32 v139, v140, v141
	v_cvt_pk_bf16_f32 v140, v142, v143
	s_addc_u32 s55, s17, 0
	v_lshl_add_u64 v[142:143], v[156:157], 0, v[0:1]
	v_cvt_pk_bf16_f32 v141, v144, v145
	v_lshl_add_u64 v[142:143], v[142:143], 1, s[54:55]
	global_store_dwordx4 v[142:143], v[138:141], off offset:256 nt

.LBB0_487:
	s_add_u32 s54, s16, s15
	v_cvt_pk_bf16_f32 v138, v138, v139
	v_cvt_pk_bf16_f32 v139, v140, v141
	v_cvt_pk_bf16_f32 v140, v142, v143
	s_addc_u32 s55, s17, 0
	v_lshl_add_u64 v[142:143], v[158:159], 0, v[0:1]
	v_cvt_pk_bf16_f32 v141, v144, v145
	v_lshl_add_u64 v[142:143], v[142:143], 1, s[54:55]
	global_store_dwordx4 v[142:143], v[138:141], off offset:256 nt

.LBB0_491:
	s_add_u32 s54, s16, s15
	v_cvt_pk_bf16_f32 v138, v138, v139
	v_cvt_pk_bf16_f32 v139, v140, v141
	v_cvt_pk_bf16_f32 v140, v142, v143
	s_addc_u32 s55, s17, 0
	v_lshl_add_u64 v[142:143], v[160:161], 0, v[0:1]
	v_cvt_pk_bf16_f32 v141, v144, v145
	v_lshl_add_u64 v[142:143], v[142:143], 1, s[54:55]
	global_store_dwordx4 v[142:143], v[138:141], off offset:256 nt

.LBB0_495:
	s_add_u32 s48, s16, s15
	v_cvt_pk_bf16_f32 v138, v138, v139
	v_cvt_pk_bf16_f32 v139, v140, v141
	v_cvt_pk_bf16_f32 v140, v142, v143
	s_addc_u32 s49, s17, 0
	v_lshl_add_u64 v[142:143], v[146:147], 0, v[0:1]
	v_cvt_pk_bf16_f32 v141, v144, v145
	v_lshl_add_u64 v[142:143], v[142:143], 1, s[48:49]
	global_store_dwordx4 v[142:143], v[138:141], off offset:256 nt
	s_branch .LBB0_462
